# GEMM K-loops: first K-iteration from a copy whose first MFMA per accumulator takes C = 0; the 128 accumulator clears per unit deleted
# speedup vs baseline: 1.0148x; 1.0082x over previous
; #define PG8_STAGE(bufoff, gbase, voff) do { _Pragma("unroll") for (int _i = 0; _i < 2; ++_i) \
;         __builtin_amdgcn_global_load_lds((const unsigned*)((const char*)(gbase) + (voff)[_i]), (PG8_LAS unsigned*)(lds + (bufoff) + ldsw + _i * 8192), 16, 0, 0); } while (0)
; #define PG8_LDA(dst, b, h) do { _Pragma("unroll") for (int m = 0; m < 4; ++m) _Pragma("unroll") for (int k = 0; k < 2; ++k) dst[m][k] = *(const PG8_LAS bf16x8*)(lds + PG8_SA(b, h) + aoff + m * 2048 + k * 1024); } while (0)
; #define PG8_LDB(dst, b, h) do { _Pragma("unroll") for (int n = 0; n < 2; ++n) _Pragma("unroll") for (int k = 0; k < 2; ++k) dst[n][k] = *(const PG8_LAS bf16x8*)(lds + PG8_SB(b, h) + boff + n * 2048 + k * 1024); } while (0)
; #define PG8_WAIT_V(n) asm volatile("s_waitcnt vmcnt(" #n ")" ::: "memory")
; #define PG8_WAIT_L(n) asm volatile("s_waitcnt lgkmcnt(" #n ")" ::: "memory")
; #define PG8_BAR __builtin_amdgcn_s_barrier()
; template <class Epi, class Sched, bool ALIGN_EPI = false, bool SP2 = false>
; __device__ __forceinline__ void gemm_phase(PG8_LAS unsigned char* lds, const Gemm g, const Sched& S, const Epi& E) {
;     ...
;         for (int t = 0; t < nt; t += 2) {
;             const bool last = (t == nt - 2);
;             const char* a1 = cA + (size_t)(t + 1) * kstep;
;             const char* a2 = last ? nA : cA + (size_t)(t + 2) * kstep; const char* b2 = last ? nB : cB + (size_t)(t + 2) * kstep;
;             const char* a3 = a2 + kstep; const char* b3 = b2 + kstep;
;             if (last && has_next) S.a_ready(nxt);
;             if constexpr (SP2) {
;             PG8_LDB(B0, 0, 0); PG8_LDB(B1, 0, 1); PG8_SCHED; PG8_LDA(At, 0, 0); PG8_STAGE(PG8_SA(1, 1), a1 + hstep, voffA);
;             PG8_WAIT_V(8); PG8_WAIT_L(0); PG8_BAR; PG8_MMA(0, 0, At, B0); PG8_MMA(0, 1, At, B1); PG8_BAR; PG8_SCHED;
;             PG8_LDA(At, 0, 1); PG8_STAGE(PG8_SB(0, 0), b2, voffB); PG8_STAGE(PG8_SB(0, 1), b2 + hstep, voffB); PG8_STAGE(PG8_SA(0, 0), a2, voffA);
;             PG8_WAIT_V(8); PG8_WAIT_L(0); PG8_BAR; PG8_MMA(1, 0, At, B0); PG8_MMA(1, 1, At, B1); PG8_BAR; PG8_SCHED;
;     ...
; #pragma unroll
;         for (int a = 0; a < 2; ++a)
; #pragma unroll
;             for (int b = 0; b < 2; ++b)
; #pragma unroll
;                 for (int m = 0; m < 4; ++m)
; #pragma unroll
;                     for (int n = 0; n < 2; ++n) acc[a][b][m][n] = (f32x4){0.f, 0.f, 0.f, 0.f};
.LBB0_152:
	s_ashr_i32 s21, s20, 31
	s_lshl_b64 s[22:23], s[20:21], 19
	s_add_u32 s22, s38, s22
	s_addc_u32 s23, s39, s23
	s_and_b64 s[24:25], s[4:5], exec
	s_cselect_b32 s7, s23, s37
	s_cselect_b32 s21, s22, s36
	s_ashr_i32 s19, s18, 31
	s_lshl_b64 s[24:25], s[18:19], 19
	v_readlane_b32 s19, v255, 42
	s_add_u32 s24, s19, s24
	v_readlane_b32 s19, v255, 43
	s_addc_u32 s25, s19, s25
	s_and_b64 s[28:29], s[4:5], exec
	s_cselect_b32 s19, s25, s43
	s_cselect_b32 s28, s24, s42
	s_add_u32 s36, s36, 0x40080
	s_addc_u32 s37, s37, 0
	s_add_u32 s29, s42, 0x100
	s_addc_u32 s60, s43, 0
	s_mov_b32 s68, -2
	s_add_u32 s42, s36, 0xfffc0080
	s_addc_u32 s43, s37, -1
	s_add_i32 s86, 0, 0x10000
	s_cmp_eq_u32 s68, 12
	s_cselect_b32 s45, s7, s43
	s_cselect_b32 s44, s21, s42
	s_cselect_b32 s43, s19, s60
	s_cselect_b32 s42, s28, s29
	s_add_i32 s90, 0, 0x14000
	v_add_u32_e32 v140, s86, v182
	v_add_u32_e32 v176, s90, v182
	ds_read_b128 v[128:131], v140
	ds_read_b128 v[132:135], v140 offset:1024
	ds_read_b128 v[136:139], v140 offset:2048
	ds_read_b128 v[140:143], v140 offset:3072
	ds_read_b128 v[144:147], v176
	ds_read_b128 v[148:151], v176 offset:1024
	ds_read_b128 v[172:175], v176 offset:2048
	ds_read_b128 v[176:179], v176 offset:3072
	v_lshl_add_u64 v[236:237], s[36:37], 0, v[166:167]
	s_add_i32 m0, s69, 0xc000
	ds_read_b128 v[192:195], v157
	ds_read_b128 v[196:199], v157 offset:1024
	ds_read_b128 v[200:203], v157 offset:2048
	ds_read_b128 v[204:207], v157 offset:3072
	ds_read_b128 v[208:211], v157 offset:4096
	ds_read_b128 v[224:227], v157 offset:5120
	ds_read_b128 v[228:231], v157 offset:6144
	ds_read_b128 v[232:235], v157 offset:7168
	global_load_lds_dwordx4 v[236:237], off
	v_lshl_add_u64 v[236:237], s[36:37], 0, v[168:169]
	s_add_i32 m0, s69, 0xe000
	s_nop 0
	global_load_lds_dwordx4 v[236:237], off
	s_waitcnt vmcnt(8)
	s_waitcnt lgkmcnt(0)
	s_barrier
	s_setprio 1
	s_waitcnt lgkmcnt(0)
	v_mfma_f32_16x16x32_bf16 v[124:127], v[128:131], v[192:195], 0
	v_mfma_f32_16x16x32_bf16 v[120:123], v[136:139], v[192:195], 0
	v_mfma_f32_16x16x32_bf16 v[116:119], v[128:131], v[200:203], 0
	v_mfma_f32_16x16x32_bf16 v[108:111], v[136:139], v[200:203], 0
	v_mfma_f32_16x16x32_bf16 v[100:103], v[128:131], v[208:211], 0
	v_mfma_f32_16x16x32_bf16 v[92:95], v[136:139], v[208:211], 0
	v_mfma_f32_16x16x32_bf16 v[84:87], v[128:131], v[228:231], 0
	v_mfma_f32_16x16x32_bf16 v[76:79], v[136:139], v[228:231], 0
	v_mfma_f32_16x16x32_bf16 v[124:127], v[132:135], v[196:199], v[124:127]
	v_mfma_f32_16x16x32_bf16 v[120:123], v[140:143], v[196:199], v[120:123]
	v_mfma_f32_16x16x32_bf16 v[116:119], v[132:135], v[204:207], v[116:119]
	v_mfma_f32_16x16x32_bf16 v[108:111], v[140:143], v[204:207], v[108:111]
	v_mfma_f32_16x16x32_bf16 v[100:103], v[132:135], v[224:227], v[100:103]
	v_mfma_f32_16x16x32_bf16 v[92:95], v[140:143], v[224:227], v[92:95]
	v_mfma_f32_16x16x32_bf16 v[84:87], v[132:135], v[232:235], v[84:87]
	v_mfma_f32_16x16x32_bf16 v[76:79], v[140:143], v[232:235], v[76:79]
	s_setprio 0
	s_setprio 1
	v_mfma_f32_16x16x32_bf16 v[112:115], v[144:147], v[192:195], 0
	v_mfma_f32_16x16x32_bf16 v[104:107], v[172:175], v[192:195], 0
	v_mfma_f32_16x16x32_bf16 v[96:99], v[144:147], v[200:203], 0
	v_mfma_f32_16x16x32_bf16 v[88:91], v[172:175], v[200:203], 0
	v_mfma_f32_16x16x32_bf16 v[80:83], v[144:147], v[208:211], 0
	v_mfma_f32_16x16x32_bf16 v[72:75], v[172:175], v[208:211], 0
	v_mfma_f32_16x16x32_bf16 v[68:71], v[144:147], v[228:231], 0
	v_mfma_f32_16x16x32_bf16 v[64:67], v[172:175], v[228:231], 0
	v_mfma_f32_16x16x32_bf16 v[112:115], v[148:151], v[196:199], v[112:115]
	v_mfma_f32_16x16x32_bf16 v[104:107], v[176:179], v[196:199], v[104:107]
	v_mfma_f32_16x16x32_bf16 v[96:99], v[148:151], v[204:207], v[96:99]
	v_mfma_f32_16x16x32_bf16 v[88:91], v[176:179], v[204:207], v[88:91]
	v_mfma_f32_16x16x32_bf16 v[80:83], v[148:151], v[224:227], v[80:83]
	v_mfma_f32_16x16x32_bf16 v[72:75], v[176:179], v[224:227], v[72:75]
	v_mfma_f32_16x16x32_bf16 v[68:71], v[148:151], v[232:235], v[68:71]
	v_mfma_f32_16x16x32_bf16 v[64:67], v[176:179], v[232:235], v[64:67]
	s_setprio 0
	s_barrier
	s_add_i32 s86, s86, s46
	v_lshl_add_u64 v[236:237], s[42:43], 0, v[154:155]
	s_mov_b32 m0, s86
	ds_read_b128 v[192:195], v157 offset:16384
	ds_read_b128 v[196:199], v157 offset:17408
	ds_read_b128 v[200:203], v157 offset:18432
	ds_read_b128 v[204:207], v157 offset:19456
	ds_read_b128 v[208:211], v157 offset:20480
	ds_read_b128 v[224:227], v157 offset:21504
	ds_read_b128 v[228:231], v157 offset:22528
	ds_read_b128 v[232:235], v157 offset:23552
	global_load_lds_dwordx4 v[236:237], off
	s_add_i32 m0, s86, 0x2000
	s_add_u32 s86, s42, 0x40000
	v_lshl_add_u64 v[238:239], s[42:43], 0, v[152:153]
	s_addc_u32 s87, s43, 0
	s_add_i32 s90, s90, s46
	global_load_lds_dwordx4 v[238:239], off
	v_lshl_add_u64 v[240:241], s[86:87], 0, v[154:155]
	s_mov_b32 m0, s90
	v_lshl_add_u64 v[242:243], s[44:45], 0, v[152:153]
	global_load_lds_dwordx4 v[240:241], off
	v_lshl_add_u64 v[240:241], s[86:87], 0, v[152:153]
	s_add_i32 m0, s90, 0x2000
	s_nop 0
	global_load_lds_dwordx4 v[240:241], off
	v_lshl_add_u64 v[240:241], s[44:45], 0, v[154:155]
	s_mov_b32 m0, s69
	s_nop 0
	global_load_lds_dwordx4 v[240:241], off
	s_mov_b32 m0, s70
	s_nop 0
	global_load_lds_dwordx4 v[242:243], off
	s_waitcnt vmcnt(8)
	s_waitcnt lgkmcnt(0)
	s_barrier
; #define PG8_STAGE(bufoff, gbase, voff) do { _Pragma("unroll") for (int _i = 0; _i < 2; ++_i) \
;         __builtin_amdgcn_global_load_lds((const unsigned*)((const char*)(gbase) + (voff)[_i]), (PG8_LAS unsigned*)(lds + (bufoff) + ldsw + _i * 8192), 16, 0, 0); } while (0)
; #define PG8_LDA(dst, b, h) do { _Pragma("unroll") for (int m = 0; m < 4; ++m) _Pragma("unroll") for (int k = 0; k < 2; ++k) dst[m][k] = *(const PG8_LAS bf16x8*)(lds + PG8_SA(b, h) + aoff + m * 2048 + k * 1024); } while (0)
; #define PG8_LDB(dst, b, h) do { _Pragma("unroll") for (int n = 0; n < 2; ++n) _Pragma("unroll") for (int k = 0; k < 2; ++k) dst[n][k] = *(const PG8_LAS bf16x8*)(lds + PG8_SB(b, h) + boff + n * 2048 + k * 1024); } while (0)
; #define PG8_MMA(ai, bj, At, Bt) do { __builtin_amdgcn_s_setprio(1); _Pragma("unroll") for (int m = 0; m < 4; ++m) _Pragma("unroll") for (int n = 0; n < 2; ++n) _Pragma("unroll") for (int k = 0; k < 2; ++k) \
;         acc[ai][bj][m][n] = __builtin_amdgcn_mfma_f32_16x16x32_bf16(Bt[n][k], At[m][k], acc[ai][bj][m][n], 0, 0, 0); __builtin_amdgcn_s_setprio(0); } while (0)
; #define PG8_WAIT_V(n) asm volatile("s_waitcnt vmcnt(" #n ")" ::: "memory")
; template <class Epi, class Sched, bool ALIGN_EPI = false, bool SP2 = false>
; __device__ __forceinline__ void gemm_phase(PG8_LAS unsigned char* lds, const Gemm g, const Sched& S, const Epi& E) {
;     ...
;             PG8_LDB(B0, 0, 0); PG8_LDB(B1, 0, 1); PG8_SCHED; PG8_LDA(At, 0, 0); PG8_STAGE(PG8_SA(1, 1), a1 + hstep, voffA);
;             PG8_WAIT_V(8); PG8_WAIT_L(0); PG8_BAR; PG8_MMA(0, 0, At, B0); PG8_MMA(0, 1, At, B1); PG8_BAR; PG8_SCHED;
;             PG8_LDA(At, 0, 1); PG8_STAGE(PG8_SB(0, 0), b2, voffB); PG8_STAGE(PG8_SB(0, 1), b2 + hstep, voffB); PG8_STAGE(PG8_SA(0, 0), a2, voffA);
;             PG8_WAIT_V(8); PG8_WAIT_L(0); PG8_BAR; PG8_MMA(1, 0, At, B0); PG8_MMA(1, 1, At, B1); PG8_BAR; PG8_SCHED;
;             PG8_LDB(B0, 1, 0); PG8_LDB(B1, 1, 1); PG8_SCHED; PG8_LDA(At, 1, 0); PG8_STAGE(PG8_SA(0, 1), a2 + hstep, voffA);
;             PG8_WAIT_V(8); PG8_WAIT_L(0); PG8_BAR; PG8_MMA(0, 0, At, B0); PG8_MMA(0, 1, At, B1); PG8_BAR; PG8_SCHED;
;             PG8_LDA(At, 1, 1); PG8_STAGE(PG8_SB(1, 0), b3, voffB); PG8_STAGE(PG8_SB(1, 1), b3 + hstep, voffB); PG8_STAGE(PG8_SA(1, 0), a3, voffA);
;             PG8_WAIT_V(8); PG8_WAIT_L(0); PG8_BAR; PG8_MMA(1, 0, At, B0); PG8_MMA(1, 1, At, B1); PG8_BAR; PG8_SCHED;
	s_setprio 1
	s_waitcnt lgkmcnt(0)
	v_mfma_f32_16x16x32_bf16 v[60:63], v[128:131], v[192:195], 0
	v_mfma_f32_16x16x32_bf16 v[56:59], v[136:139], v[192:195], 0
	v_mfma_f32_16x16x32_bf16 v[52:55], v[128:131], v[200:203], 0
	v_mfma_f32_16x16x32_bf16 v[44:47], v[136:139], v[200:203], 0
	v_mfma_f32_16x16x32_bf16 v[36:39], v[128:131], v[208:211], 0
	v_mfma_f32_16x16x32_bf16 v[28:31], v[136:139], v[208:211], 0
	v_mfma_f32_16x16x32_bf16 v[20:23], v[128:131], v[228:231], 0
	v_mfma_f32_16x16x32_bf16 v[12:15], v[136:139], v[228:231], 0
	v_mfma_f32_16x16x32_bf16 v[60:63], v[132:135], v[196:199], v[60:63]
	v_mfma_f32_16x16x32_bf16 v[56:59], v[140:143], v[196:199], v[56:59]
	v_mfma_f32_16x16x32_bf16 v[52:55], v[132:135], v[204:207], v[52:55]
	v_mfma_f32_16x16x32_bf16 v[44:47], v[140:143], v[204:207], v[44:47]
	v_mfma_f32_16x16x32_bf16 v[36:39], v[132:135], v[224:227], v[36:39]
	v_mfma_f32_16x16x32_bf16 v[28:31], v[140:143], v[224:227], v[28:31]
	v_mfma_f32_16x16x32_bf16 v[20:23], v[132:135], v[232:235], v[20:23]
	v_mfma_f32_16x16x32_bf16 v[12:15], v[140:143], v[232:235], v[12:15]
	s_setprio 0
	s_setprio 1
	v_mfma_f32_16x16x32_bf16 v[48:51], v[144:147], v[192:195], 0
	v_mfma_f32_16x16x32_bf16 v[40:43], v[172:175], v[192:195], 0
	v_mfma_f32_16x16x32_bf16 v[32:35], v[144:147], v[200:203], 0
	v_mfma_f32_16x16x32_bf16 v[24:27], v[172:175], v[200:203], 0
	v_mfma_f32_16x16x32_bf16 v[16:19], v[144:147], v[208:211], 0
	v_mfma_f32_16x16x32_bf16 v[8:11], v[172:175], v[208:211], 0
	v_mfma_f32_16x16x32_bf16 v[4:7], v[144:147], v[228:231], 0
	v_mfma_f32_16x16x32_bf16 v[0:3], v[172:175], v[228:231], 0
	v_mfma_f32_16x16x32_bf16 v[48:51], v[148:151], v[196:199], v[48:51]
	v_mfma_f32_16x16x32_bf16 v[40:43], v[176:179], v[196:199], v[40:43]
	v_mfma_f32_16x16x32_bf16 v[32:35], v[148:151], v[204:207], v[32:35]
	v_mfma_f32_16x16x32_bf16 v[24:27], v[176:179], v[204:207], v[24:27]
	v_mfma_f32_16x16x32_bf16 v[16:19], v[148:151], v[224:227], v[16:19]
	v_mfma_f32_16x16x32_bf16 v[8:11], v[176:179], v[224:227], v[8:11]
	v_mfma_f32_16x16x32_bf16 v[4:7], v[148:151], v[232:235], v[4:7]
	v_mfma_f32_16x16x32_bf16 v[0:3], v[176:179], v[232:235], v[0:3]
	s_setprio 0
	s_barrier
	s_add_i32 s86, 0, 0x18000
	s_add_i32 s87, 0, 0x1c000
	v_add_u32_e32 v140, s86, v182
	v_add_u32_e32 v176, s87, v182
	ds_read_b128 v[128:131], v140
	ds_read_b128 v[132:135], v140 offset:1024
	ds_read_b128 v[136:139], v140 offset:2048
	ds_read_b128 v[140:143], v140 offset:3072
	ds_read_b128 v[144:147], v176
	ds_read_b128 v[148:151], v176 offset:1024
	ds_read_b128 v[172:175], v176 offset:2048
	ds_read_b128 v[176:179], v176 offset:3072
	s_add_u32 s44, s44, 0x40000
	s_addc_u32 s45, s45, 0
	s_mov_b32 m0, s71
	v_lshl_add_u64 v[244:245], s[44:45], 0, v[154:155]
	ds_read_b128 v[192:195], v157 offset:32768
	ds_read_b128 v[196:199], v157 offset:33792
	ds_read_b128 v[200:203], v157 offset:34816
	ds_read_b128 v[204:207], v157 offset:35840
	ds_read_b128 v[208:211], v157 offset:36864
	ds_read_b128 v[224:227], v157 offset:37888
	ds_read_b128 v[228:231], v157 offset:38912
	ds_read_b128 v[232:235], v157 offset:39936
	global_load_lds_dwordx4 v[244:245], off
	v_lshl_add_u64 v[244:245], s[44:45], 0, v[152:153]
	s_mov_b32 m0, s72
	s_nop 0
	global_load_lds_dwordx4 v[244:245], off
	s_waitcnt vmcnt(8)
	s_waitcnt lgkmcnt(0)
	s_barrier
	s_setprio 1
	s_waitcnt lgkmcnt(0)
	v_mfma_f32_16x16x32_bf16 v[124:127], v[128:131], v[192:195], v[124:127]
	v_mfma_f32_16x16x32_bf16 v[120:123], v[136:139], v[192:195], v[120:123]
	v_mfma_f32_16x16x32_bf16 v[116:119], v[128:131], v[200:203], v[116:119]
	v_mfma_f32_16x16x32_bf16 v[108:111], v[136:139], v[200:203], v[108:111]
	v_mfma_f32_16x16x32_bf16 v[100:103], v[128:131], v[208:211], v[100:103]
	v_mfma_f32_16x16x32_bf16 v[92:95], v[136:139], v[208:211], v[92:95]
	v_mfma_f32_16x16x32_bf16 v[84:87], v[128:131], v[228:231], v[84:87]
	v_mfma_f32_16x16x32_bf16 v[76:79], v[136:139], v[228:231], v[76:79]
	v_mfma_f32_16x16x32_bf16 v[124:127], v[132:135], v[196:199], v[124:127]
	v_mfma_f32_16x16x32_bf16 v[120:123], v[140:143], v[196:199], v[120:123]
	v_mfma_f32_16x16x32_bf16 v[116:119], v[132:135], v[204:207], v[116:119]
	v_mfma_f32_16x16x32_bf16 v[108:111], v[140:143], v[204:207], v[108:111]
	v_mfma_f32_16x16x32_bf16 v[100:103], v[132:135], v[224:227], v[100:103]
	v_mfma_f32_16x16x32_bf16 v[92:95], v[140:143], v[224:227], v[92:95]
	v_mfma_f32_16x16x32_bf16 v[84:87], v[132:135], v[232:235], v[84:87]
	v_mfma_f32_16x16x32_bf16 v[76:79], v[140:143], v[232:235], v[76:79]
	s_setprio 0
	s_setprio 1
	v_mfma_f32_16x16x32_bf16 v[112:115], v[144:147], v[192:195], v[112:115]
	v_mfma_f32_16x16x32_bf16 v[104:107], v[172:175], v[192:195], v[104:107]
	v_mfma_f32_16x16x32_bf16 v[96:99], v[144:147], v[200:203], v[96:99]
	v_mfma_f32_16x16x32_bf16 v[88:91], v[172:175], v[200:203], v[88:91]
	v_mfma_f32_16x16x32_bf16 v[80:83], v[144:147], v[208:211], v[80:83]
	v_mfma_f32_16x16x32_bf16 v[72:75], v[172:175], v[208:211], v[72:75]
	v_mfma_f32_16x16x32_bf16 v[68:71], v[144:147], v[228:231], v[68:71]
	v_mfma_f32_16x16x32_bf16 v[64:67], v[172:175], v[228:231], v[64:67]
	v_mfma_f32_16x16x32_bf16 v[112:115], v[148:151], v[196:199], v[112:115]
	v_mfma_f32_16x16x32_bf16 v[104:107], v[176:179], v[196:199], v[104:107]
	v_mfma_f32_16x16x32_bf16 v[96:99], v[148:151], v[204:207], v[96:99]
	v_mfma_f32_16x16x32_bf16 v[88:91], v[176:179], v[204:207], v[88:91]
	v_mfma_f32_16x16x32_bf16 v[80:83], v[148:151], v[224:227], v[80:83]
	v_mfma_f32_16x16x32_bf16 v[72:75], v[176:179], v[224:227], v[72:75]
	v_mfma_f32_16x16x32_bf16 v[68:71], v[148:151], v[232:235], v[68:71]
	v_mfma_f32_16x16x32_bf16 v[64:67], v[176:179], v[232:235], v[64:67]
	s_setprio 0
	s_barrier
; #define PG8_STAGE(bufoff, gbase, voff) do { _Pragma("unroll") for (int _i = 0; _i < 2; ++_i) \
;         __builtin_amdgcn_global_load_lds((const unsigned*)((const char*)(gbase) + (voff)[_i]), (PG8_LAS unsigned*)(lds + (bufoff) + ldsw + _i * 8192), 16, 0, 0); } while (0)
; #define PG8_LDA(dst, b, h) do { _Pragma("unroll") for (int m = 0; m < 4; ++m) _Pragma("unroll") for (int k = 0; k < 2; ++k) dst[m][k] = *(const PG8_LAS bf16x8*)(lds + PG8_SA(b, h) + aoff + m * 2048 + k * 1024); } while (0)
; #define PG8_LDB(dst, b, h) do { _Pragma("unroll") for (int n = 0; n < 2; ++n) _Pragma("unroll") for (int k = 0; k < 2; ++k) dst[n][k] = *(const PG8_LAS bf16x8*)(lds + PG8_SB(b, h) + boff + n * 2048 + k * 1024); } while (0)
; #define PG8_MMA(ai, bj, At, Bt) do { __builtin_amdgcn_s_setprio(1); _Pragma("unroll") for (int m = 0; m < 4; ++m) _Pragma("unroll") for (int n = 0; n < 2; ++n) _Pragma("unroll") for (int k = 0; k < 2; ++k) \
;         acc[ai][bj][m][n] = __builtin_amdgcn_mfma_f32_16x16x32_bf16(Bt[n][k], At[m][k], acc[ai][bj][m][n], 0, 0, 0); __builtin_amdgcn_s_setprio(0); } while (0)
; #define PG8_WAIT_V(n) asm volatile("s_waitcnt vmcnt(" #n ")" ::: "memory")
; #define PG8_WAIT_L(n) asm volatile("s_waitcnt lgkmcnt(" #n ")" ::: "memory")
; #define PG8_BAR __builtin_amdgcn_s_barrier()
; #define PG8_SCHED __builtin_amdgcn_sched_barrier(0)
; template <class Epi, class Sched, bool ALIGN_EPI = false, bool SP2 = false>
; __device__ __forceinline__ void gemm_phase(PG8_LAS unsigned char* lds, const Gemm g, const Sched& S, const Epi& E) {
;     ...
;         for (int t = 0; t < nt; t += 2) {
;             const bool last = (t == nt - 2);
;             const char* a1 = cA + (size_t)(t + 1) * kstep;
;             const char* a2 = last ? nA : cA + (size_t)(t + 2) * kstep; const char* b2 = last ? nB : cB + (size_t)(t + 2) * kstep;
;     ...
;             PG8_LDB(B0, 1, 0); PG8_LDB(B1, 1, 1); PG8_SCHED; PG8_LDA(At, 1, 0); PG8_STAGE(PG8_SA(0, 1), a2 + hstep, voffA);
;             PG8_WAIT_V(8); PG8_WAIT_L(0); PG8_BAR; PG8_MMA(0, 0, At, B0); PG8_MMA(0, 1, At, B1); PG8_BAR; PG8_SCHED;
;             PG8_LDA(At, 1, 1); PG8_STAGE(PG8_SB(1, 0), b3, voffB); PG8_STAGE(PG8_SB(1, 1), b3 + hstep, voffB); PG8_STAGE(PG8_SA(1, 0), a3, voffA);
;             PG8_WAIT_V(8); PG8_WAIT_L(0); PG8_BAR; PG8_MMA(1, 0, At, B0); PG8_MMA(1, 1, At, B1); PG8_BAR; PG8_SCHED;
	s_add_i32 s44, s86, s46
	v_lshl_add_u64 v[236:237], v[236:237], 0, s[30:31]
	s_mov_b32 m0, s44
	ds_read_b128 v[192:195], v157 offset:49152
	ds_read_b128 v[196:199], v157 offset:50176
	ds_read_b128 v[200:203], v157 offset:51200
	ds_read_b128 v[204:207], v157 offset:52224
	ds_read_b128 v[208:211], v157 offset:53248
	ds_read_b128 v[224:227], v157 offset:54272
	ds_read_b128 v[228:231], v157 offset:55296
	ds_read_b128 v[232:235], v157 offset:56320
	global_load_lds_dwordx4 v[236:237], off
	s_add_i32 m0, s44, 0x2000
	s_add_u32 s42, s42, 0x40080
	v_lshl_add_u64 v[236:237], v[238:239], 0, s[30:31]
	s_addc_u32 s43, s43, 0
	s_add_i32 s44, s87, s46
	global_load_lds_dwordx4 v[236:237], off
	v_lshl_add_u64 v[236:237], s[42:43], 0, v[154:155]
	s_mov_b32 m0, s44
	s_nop 0
	global_load_lds_dwordx4 v[236:237], off
	v_lshl_add_u64 v[236:237], s[42:43], 0, v[152:153]
	s_add_i32 m0, s44, 0x2000
	s_nop 0
	global_load_lds_dwordx4 v[236:237], off
	v_lshl_add_u64 v[236:237], v[240:241], 0, s[30:31]
	s_mov_b32 m0, s77
	s_nop 0
	global_load_lds_dwordx4 v[236:237], off
	v_lshl_add_u64 v[236:237], v[242:243], 0, s[30:31]
	s_mov_b32 m0, s78
	s_nop 0
	global_load_lds_dwordx4 v[236:237], off
	s_waitcnt vmcnt(8)
	s_waitcnt lgkmcnt(0)
	s_barrier
	s_setprio 1
	s_waitcnt lgkmcnt(0)
	v_mfma_f32_16x16x32_bf16 v[60:63], v[128:131], v[192:195], v[60:63]
	v_mfma_f32_16x16x32_bf16 v[56:59], v[136:139], v[192:195], v[56:59]
	v_mfma_f32_16x16x32_bf16 v[52:55], v[128:131], v[200:203], v[52:55]
	v_mfma_f32_16x16x32_bf16 v[44:47], v[136:139], v[200:203], v[44:47]
	v_mfma_f32_16x16x32_bf16 v[36:39], v[128:131], v[208:211], v[36:39]
	v_mfma_f32_16x16x32_bf16 v[28:31], v[136:139], v[208:211], v[28:31]
	v_mfma_f32_16x16x32_bf16 v[20:23], v[128:131], v[228:231], v[20:23]
	v_mfma_f32_16x16x32_bf16 v[12:15], v[136:139], v[228:231], v[12:15]
	v_mfma_f32_16x16x32_bf16 v[60:63], v[132:135], v[196:199], v[60:63]
	v_mfma_f32_16x16x32_bf16 v[56:59], v[140:143], v[196:199], v[56:59]
	v_mfma_f32_16x16x32_bf16 v[52:55], v[132:135], v[204:207], v[52:55]
	v_mfma_f32_16x16x32_bf16 v[44:47], v[140:143], v[204:207], v[44:47]
	v_mfma_f32_16x16x32_bf16 v[36:39], v[132:135], v[224:227], v[36:39]
	v_mfma_f32_16x16x32_bf16 v[28:31], v[140:143], v[224:227], v[28:31]
	v_mfma_f32_16x16x32_bf16 v[20:23], v[132:135], v[232:235], v[20:23]
	v_mfma_f32_16x16x32_bf16 v[12:15], v[140:143], v[232:235], v[12:15]
	s_setprio 0
	s_setprio 1
	v_mfma_f32_16x16x32_bf16 v[48:51], v[144:147], v[192:195], v[48:51]
	v_mfma_f32_16x16x32_bf16 v[40:43], v[172:175], v[192:195], v[40:43]
	v_mfma_f32_16x16x32_bf16 v[32:35], v[144:147], v[200:203], v[32:35]
	v_mfma_f32_16x16x32_bf16 v[24:27], v[172:175], v[200:203], v[24:27]
	v_mfma_f32_16x16x32_bf16 v[16:19], v[144:147], v[208:211], v[16:19]
	v_mfma_f32_16x16x32_bf16 v[8:11], v[172:175], v[208:211], v[8:11]
	v_mfma_f32_16x16x32_bf16 v[4:7], v[144:147], v[228:231], v[4:7]
	v_mfma_f32_16x16x32_bf16 v[0:3], v[172:175], v[228:231], v[0:3]
	v_mfma_f32_16x16x32_bf16 v[48:51], v[148:151], v[196:199], v[48:51]
	v_mfma_f32_16x16x32_bf16 v[40:43], v[176:179], v[196:199], v[40:43]
	v_mfma_f32_16x16x32_bf16 v[32:35], v[148:151], v[204:207], v[32:35]
	v_mfma_f32_16x16x32_bf16 v[24:27], v[176:179], v[204:207], v[24:27]
	v_mfma_f32_16x16x32_bf16 v[16:19], v[148:151], v[224:227], v[16:19]
	v_mfma_f32_16x16x32_bf16 v[8:11], v[176:179], v[224:227], v[8:11]
	v_mfma_f32_16x16x32_bf16 v[4:7], v[148:151], v[232:235], v[4:7]
	v_mfma_f32_16x16x32_bf16 v[0:3], v[176:179], v[232:235], v[0:3]
	s_setprio 0
	s_barrier
	s_add_i32 s68, s68, 2
	s_add_u32 s36, s36, 0x100
	s_addc_u32 s37, s37, 0
	s_add_u32 s29, s29, 0x100
	s_addc_u32 s60, s60, 0
	s_cmp_gt_u32 s68, 13
	s_cbranch_scc0 .LBB0_153
	s_branch .Lgzero0_done

; #define PG8_BAR __builtin_amdgcn_s_barrier()
; template <class Epi, class Sched, bool ALIGN_EPI = false, bool SP2 = false>
; __device__ __forceinline__ void gemm_phase(PG8_LAS unsigned char* lds, const Gemm g, const Sched& S, const Epi& E) {
;     ...
;         if constexpr (ALIGN_EPI) { if (wr == 0) PG8_BAR; }
;         if constexpr (!Epi::AFTER_DRAIN) { E(acc, cur, wr, wc, fr, fq); S.done(cur); }
;         if (!has_next) break;
.Lgzero0_done:
	s_and_b64 vcc, exec, s[12:13]
	s_cbranch_vccz .LBB0_156
	s_barrier

; #define PG8_STAGE(bufoff, gbase, voff) do { _Pragma("unroll") for (int _i = 0; _i < 2; ++_i) \
;         __builtin_amdgcn_global_load_lds((const unsigned*)((const char*)(gbase) + (voff)[_i]), (PG8_LAS unsigned*)(lds + (bufoff) + ldsw + _i * 8192), 16, 0, 0); } while (0)
; #define PG8_LDA(dst, b, h) do { _Pragma("unroll") for (int m = 0; m < 4; ++m) _Pragma("unroll") for (int k = 0; k < 2; ++k) dst[m][k] = *(const PG8_LAS bf16x8*)(lds + PG8_SA(b, h) + aoff + m * 2048 + k * 1024); } while (0)
; #define PG8_LDB(dst, b, h) do { _Pragma("unroll") for (int n = 0; n < 2; ++n) _Pragma("unroll") for (int k = 0; k < 2; ++k) dst[n][k] = *(const PG8_LAS bf16x8*)(lds + PG8_SB(b, h) + boff + n * 2048 + k * 1024); } while (0)
; #define PG8_WAIT_V(n) asm volatile("s_waitcnt vmcnt(" #n ")" ::: "memory")
; #define PG8_WAIT_L(n) asm volatile("s_waitcnt lgkmcnt(" #n ")" ::: "memory")
; #define PG8_BAR __builtin_amdgcn_s_barrier()
; template <class Epi, class Sched, bool ALIGN_EPI = false, bool SP2 = false>
; __device__ __forceinline__ void gemm_phase(PG8_LAS unsigned char* lds, const Gemm g, const Sched& S, const Epi& E) {
;     ...
;         for (int t = 0; t < nt; t += 2) {
;             const bool last = (t == nt - 2);
;             const char* a1 = cA + (size_t)(t + 1) * kstep;
;             const char* a2 = last ? nA : cA + (size_t)(t + 2) * kstep; const char* b2 = last ? nB : cB + (size_t)(t + 2) * kstep;
;             const char* a3 = a2 + kstep; const char* b3 = b2 + kstep;
;             if (last && has_next) S.a_ready(nxt);
;             if constexpr (SP2) {
;             PG8_LDB(B0, 0, 0); PG8_LDB(B1, 0, 1); PG8_SCHED; PG8_LDA(At, 0, 0); PG8_STAGE(PG8_SA(1, 1), a1 + hstep, voffA);
;             PG8_WAIT_V(8); PG8_WAIT_L(0); PG8_BAR; PG8_MMA(0, 0, At, B0); PG8_MMA(0, 1, At, B1); PG8_BAR; PG8_SCHED;
;             PG8_LDA(At, 0, 1); PG8_STAGE(PG8_SB(0, 0), b2, voffB); PG8_STAGE(PG8_SB(0, 1), b2 + hstep, voffB); PG8_STAGE(PG8_SA(0, 0), a2, voffA);
;             PG8_WAIT_V(8); PG8_WAIT_L(0); PG8_BAR; PG8_MMA(1, 0, At, B0); PG8_MMA(1, 1, At, B1); PG8_BAR; PG8_SCHED;
;     ...
; #pragma unroll
;         for (int a = 0; a < 2; ++a)
; #pragma unroll
;             for (int b = 0; b < 2; ++b)
; #pragma unroll
;                 for (int m = 0; m < 4; ++m)
; #pragma unroll
;                     for (int n = 0; n < 2; ++n) acc[a][b][m][n] = (f32x4){0.f, 0.f, 0.f, 0.f};
.LBB0_373:
	s_ashr_i32 s19, s18, 31
	s_lshl_b64 s[20:21], s[18:19], 19
	s_add_u32 s20, s38, s20
	s_addc_u32 s21, s39, s21
	s_and_b64 s[22:23], s[6:7], exec
	s_cselect_b32 s19, s21, s25
	s_cselect_b32 s71, s20, s24
	s_ashr_i32 s17, s16, 31
	s_lshl_b64 s[22:23], s[16:17], 19
	s_add_u32 s22, s28, s22
	s_addc_u32 s23, s29, s23
	s_and_b64 s[42:43], s[6:7], exec
	s_cselect_b32 s17, s23, s37
	s_cselect_b32 s72, s22, s36
	s_add_u32 s24, s24, 0x40080
	s_addc_u32 s25, s25, 0
	s_add_u32 s73, s36, 0x100
	s_addc_u32 s76, s37, 0
	s_mov_b32 s77, -2
	s_add_u32 s36, s24, 0xfffc0080
	s_addc_u32 s37, s25, -1
	s_add_i32 s78, 0, 0x10000
	s_cmp_eq_u32 s77, 12
	s_cselect_b32 s43, s19, s37
	s_cselect_b32 s42, s71, s36
	s_cselect_b32 s37, s17, s76
	s_cselect_b32 s36, s72, s73
	s_add_i32 s80, 0, 0x14000
	v_add_u32_e32 v68, s78, v153
	v_add_u32_e32 v150, s80, v153
	ds_read_b128 v[48:51], v68
	ds_read_b128 v[52:55], v68 offset:1024
	ds_read_b128 v[64:67], v68 offset:2048
	ds_read_b128 v[68:71], v68 offset:3072
	ds_read_b128 v[156:159], v150
	ds_read_b128 v[160:163], v150 offset:1024
	ds_read_b128 v[164:167], v150 offset:2048
	ds_read_b128 v[168:171], v150 offset:3072
	v_lshl_add_u64 v[150:151], s[24:25], 0, v[146:147]
	s_add_i32 m0, s45, 0xc000
	ds_read_b128 v[172:175], v155
	ds_read_b128 v[176:179], v155 offset:1024
	ds_read_b128 v[180:183], v155 offset:2048
	ds_read_b128 v[190:193], v155 offset:3072
	ds_read_b128 v[194:197], v155 offset:4096
	ds_read_b128 v[198:201], v155 offset:5120
	ds_read_b128 v[202:205], v155 offset:6144
	ds_read_b128 v[206:209], v155 offset:7168
	global_load_lds_dwordx4 v[150:151], off
	v_lshl_add_u64 v[150:151], s[24:25], 0, v[148:149]
	s_add_i32 m0, s45, 0xe000
	s_nop 0
	global_load_lds_dwordx4 v[150:151], off
	s_waitcnt vmcnt(8)
	s_waitcnt lgkmcnt(0)
	s_barrier
	s_setprio 1
	s_waitcnt lgkmcnt(0)
	v_mfma_f32_16x16x32_bf16 v[140:143], v[48:51], v[172:175], 0
	v_mfma_f32_16x16x32_bf16 v[136:139], v[64:67], v[172:175], 0
	v_mfma_f32_16x16x32_bf16 v[124:127], v[48:51], v[180:183], 0
	v_mfma_f32_16x16x32_bf16 v[120:123], v[64:67], v[180:183], 0
	v_mfma_f32_16x16x32_bf16 v[108:111], v[48:51], v[194:197], 0
	v_mfma_f32_16x16x32_bf16 v[104:107], v[64:67], v[194:197], 0
	v_mfma_f32_16x16x32_bf16 v[92:95], v[48:51], v[202:205], 0
	v_mfma_f32_16x16x32_bf16 v[88:91], v[64:67], v[202:205], 0
	v_mfma_f32_16x16x32_bf16 v[140:143], v[52:55], v[176:179], v[140:143]
	v_mfma_f32_16x16x32_bf16 v[136:139], v[68:71], v[176:179], v[136:139]
	v_mfma_f32_16x16x32_bf16 v[124:127], v[52:55], v[190:193], v[124:127]
	v_mfma_f32_16x16x32_bf16 v[120:123], v[68:71], v[190:193], v[120:123]
	v_mfma_f32_16x16x32_bf16 v[108:111], v[52:55], v[198:201], v[108:111]
	v_mfma_f32_16x16x32_bf16 v[104:107], v[68:71], v[198:201], v[104:107]
	v_mfma_f32_16x16x32_bf16 v[92:95], v[52:55], v[206:209], v[92:95]
	v_mfma_f32_16x16x32_bf16 v[88:91], v[68:71], v[206:209], v[88:91]
	s_setprio 0
	s_setprio 1
	v_mfma_f32_16x16x32_bf16 v[132:135], v[156:159], v[172:175], 0
	v_mfma_f32_16x16x32_bf16 v[128:131], v[164:167], v[172:175], 0
	v_mfma_f32_16x16x32_bf16 v[116:119], v[156:159], v[180:183], 0
	v_mfma_f32_16x16x32_bf16 v[112:115], v[164:167], v[180:183], 0
	v_mfma_f32_16x16x32_bf16 v[100:103], v[156:159], v[194:197], 0
	v_mfma_f32_16x16x32_bf16 v[96:99], v[164:167], v[194:197], 0
	v_mfma_f32_16x16x32_bf16 v[84:87], v[156:159], v[202:205], 0
	v_mfma_f32_16x16x32_bf16 v[80:83], v[164:167], v[202:205], 0
	v_mfma_f32_16x16x32_bf16 v[132:135], v[160:163], v[176:179], v[132:135]
	v_mfma_f32_16x16x32_bf16 v[128:131], v[168:171], v[176:179], v[128:131]
	v_mfma_f32_16x16x32_bf16 v[116:119], v[160:163], v[190:193], v[116:119]
	v_mfma_f32_16x16x32_bf16 v[112:115], v[168:171], v[190:193], v[112:115]
	v_mfma_f32_16x16x32_bf16 v[100:103], v[160:163], v[198:201], v[100:103]
	v_mfma_f32_16x16x32_bf16 v[96:99], v[168:171], v[198:201], v[96:99]
	v_mfma_f32_16x16x32_bf16 v[84:87], v[160:163], v[206:209], v[84:87]
	v_mfma_f32_16x16x32_bf16 v[80:83], v[168:171], v[206:209], v[80:83]
	s_setprio 0
	s_barrier
	s_add_i32 s78, s78, s44
	v_lshl_add_u64 v[150:151], s[36:37], 0, v[184:185]
	s_mov_b32 m0, s78
	ds_read_b128 v[172:175], v155 offset:16384
	ds_read_b128 v[176:179], v155 offset:17408
	ds_read_b128 v[180:183], v155 offset:18432
	ds_read_b128 v[190:193], v155 offset:19456
	ds_read_b128 v[194:197], v155 offset:20480
	ds_read_b128 v[198:201], v155 offset:21504
	ds_read_b128 v[202:205], v155 offset:22528
	ds_read_b128 v[206:209], v155 offset:23552
	global_load_lds_dwordx4 v[150:151], off
	s_add_i32 m0, s78, 0x2000
	s_add_u32 s78, s36, 0x40000
	v_lshl_add_u64 v[186:187], s[36:37], 0, v[144:145]
	s_addc_u32 s79, s37, 0
	s_add_i32 s80, s80, s44
	global_load_lds_dwordx4 v[186:187], off
	v_lshl_add_u64 v[188:189], s[78:79], 0, v[184:185]
	s_mov_b32 m0, s80
	v_lshl_add_u64 v[210:211], s[42:43], 0, v[144:145]
	global_load_lds_dwordx4 v[188:189], off
	v_lshl_add_u64 v[188:189], s[78:79], 0, v[144:145]
	s_add_i32 m0, s80, 0x2000
	s_nop 0
	global_load_lds_dwordx4 v[188:189], off
	v_lshl_add_u64 v[188:189], s[42:43], 0, v[184:185]
	s_mov_b32 m0, s45
	s_nop 0
	global_load_lds_dwordx4 v[188:189], off
	s_mov_b32 m0, s46
	s_nop 0
	global_load_lds_dwordx4 v[210:211], off
	s_waitcnt vmcnt(8)
	s_waitcnt lgkmcnt(0)
	s_barrier
; #define PG8_STAGE(bufoff, gbase, voff) do { _Pragma("unroll") for (int _i = 0; _i < 2; ++_i) \
;         __builtin_amdgcn_global_load_lds((const unsigned*)((const char*)(gbase) + (voff)[_i]), (PG8_LAS unsigned*)(lds + (bufoff) + ldsw + _i * 8192), 16, 0, 0); } while (0)
; #define PG8_LDA(dst, b, h) do { _Pragma("unroll") for (int m = 0; m < 4; ++m) _Pragma("unroll") for (int k = 0; k < 2; ++k) dst[m][k] = *(const PG8_LAS bf16x8*)(lds + PG8_SA(b, h) + aoff + m * 2048 + k * 1024); } while (0)
; #define PG8_LDB(dst, b, h) do { _Pragma("unroll") for (int n = 0; n < 2; ++n) _Pragma("unroll") for (int k = 0; k < 2; ++k) dst[n][k] = *(const PG8_LAS bf16x8*)(lds + PG8_SB(b, h) + boff + n * 2048 + k * 1024); } while (0)
; #define PG8_MMA(ai, bj, At, Bt) do { __builtin_amdgcn_s_setprio(1); _Pragma("unroll") for (int m = 0; m < 4; ++m) _Pragma("unroll") for (int n = 0; n < 2; ++n) _Pragma("unroll") for (int k = 0; k < 2; ++k) \
;         acc[ai][bj][m][n] = __builtin_amdgcn_mfma_f32_16x16x32_bf16(Bt[n][k], At[m][k], acc[ai][bj][m][n], 0, 0, 0); __builtin_amdgcn_s_setprio(0); } while (0)
; #define PG8_WAIT_V(n) asm volatile("s_waitcnt vmcnt(" #n ")" ::: "memory")
; template <class Epi, class Sched, bool ALIGN_EPI = false, bool SP2 = false>
; __device__ __forceinline__ void gemm_phase(PG8_LAS unsigned char* lds, const Gemm g, const Sched& S, const Epi& E) {
;     ...
;             PG8_LDB(B0, 0, 0); PG8_LDB(B1, 0, 1); PG8_SCHED; PG8_LDA(At, 0, 0); PG8_STAGE(PG8_SA(1, 1), a1 + hstep, voffA);
;             PG8_WAIT_V(8); PG8_WAIT_L(0); PG8_BAR; PG8_MMA(0, 0, At, B0); PG8_MMA(0, 1, At, B1); PG8_BAR; PG8_SCHED;
;             PG8_LDA(At, 0, 1); PG8_STAGE(PG8_SB(0, 0), b2, voffB); PG8_STAGE(PG8_SB(0, 1), b2 + hstep, voffB); PG8_STAGE(PG8_SA(0, 0), a2, voffA);
;             PG8_WAIT_V(8); PG8_WAIT_L(0); PG8_BAR; PG8_MMA(1, 0, At, B0); PG8_MMA(1, 1, At, B1); PG8_BAR; PG8_SCHED;
;             PG8_LDB(B0, 1, 0); PG8_LDB(B1, 1, 1); PG8_SCHED; PG8_LDA(At, 1, 0); PG8_STAGE(PG8_SA(0, 1), a2 + hstep, voffA);
;             PG8_WAIT_V(8); PG8_WAIT_L(0); PG8_BAR; PG8_MMA(0, 0, At, B0); PG8_MMA(0, 1, At, B1); PG8_BAR; PG8_SCHED;
;             PG8_LDA(At, 1, 1); PG8_STAGE(PG8_SB(1, 0), b3, voffB); PG8_STAGE(PG8_SB(1, 1), b3 + hstep, voffB); PG8_STAGE(PG8_SA(1, 0), a3, voffA);
;             PG8_WAIT_V(8); PG8_WAIT_L(0); PG8_BAR; PG8_MMA(1, 0, At, B0); PG8_MMA(1, 1, At, B1); PG8_BAR; PG8_SCHED;
	s_setprio 1
	s_waitcnt lgkmcnt(0)
	v_mfma_f32_16x16x32_bf16 v[76:79], v[48:51], v[172:175], 0
	v_mfma_f32_16x16x32_bf16 v[72:75], v[64:67], v[172:175], 0
	v_mfma_f32_16x16x32_bf16 v[44:47], v[48:51], v[180:183], 0
	v_mfma_f32_16x16x32_bf16 v[40:43], v[64:67], v[180:183], 0
	v_mfma_f32_16x16x32_bf16 v[28:31], v[48:51], v[194:197], 0
	v_mfma_f32_16x16x32_bf16 v[24:27], v[64:67], v[194:197], 0
	v_mfma_f32_16x16x32_bf16 v[12:15], v[48:51], v[202:205], 0
	v_mfma_f32_16x16x32_bf16 v[8:11], v[64:67], v[202:205], 0
	v_mfma_f32_16x16x32_bf16 v[76:79], v[52:55], v[176:179], v[76:79]
	v_mfma_f32_16x16x32_bf16 v[72:75], v[68:71], v[176:179], v[72:75]
	v_mfma_f32_16x16x32_bf16 v[44:47], v[52:55], v[190:193], v[44:47]
	v_mfma_f32_16x16x32_bf16 v[40:43], v[68:71], v[190:193], v[40:43]
	v_mfma_f32_16x16x32_bf16 v[28:31], v[52:55], v[198:201], v[28:31]
	v_mfma_f32_16x16x32_bf16 v[24:27], v[68:71], v[198:201], v[24:27]
	v_mfma_f32_16x16x32_bf16 v[12:15], v[52:55], v[206:209], v[12:15]
	v_mfma_f32_16x16x32_bf16 v[8:11], v[68:71], v[206:209], v[8:11]
	s_setprio 0
	s_setprio 1
	v_mfma_f32_16x16x32_bf16 v[36:39], v[156:159], v[180:183], 0
	v_mfma_f32_16x16x32_bf16 v[32:35], v[164:167], v[180:183], 0
	v_mfma_f32_16x16x32_bf16 v[20:23], v[156:159], v[194:197], 0
	v_mfma_f32_16x16x32_bf16 v[16:19], v[164:167], v[194:197], 0
	v_mfma_f32_16x16x32_bf16 v[4:7], v[156:159], v[202:205], 0
	v_mfma_f32_16x16x32_bf16 v[0:3], v[164:167], v[202:205], 0
	v_mfma_f32_16x16x32_bf16 v[48:51], v[156:159], v[172:175], 0
	v_mfma_f32_16x16x32_bf16 v[52:55], v[164:167], v[172:175], 0
	v_mfma_f32_16x16x32_bf16 v[36:39], v[160:163], v[190:193], v[36:39]
	v_mfma_f32_16x16x32_bf16 v[32:35], v[168:171], v[190:193], v[32:35]
	v_mfma_f32_16x16x32_bf16 v[20:23], v[160:163], v[198:201], v[20:23]
	v_mfma_f32_16x16x32_bf16 v[16:19], v[168:171], v[198:201], v[16:19]
	v_mfma_f32_16x16x32_bf16 v[4:7], v[160:163], v[206:209], v[4:7]
	v_mfma_f32_16x16x32_bf16 v[0:3], v[168:171], v[206:209], v[0:3]
	v_mfma_f32_16x16x32_bf16 v[48:51], v[160:163], v[176:179], v[48:51]
	v_mfma_f32_16x16x32_bf16 v[52:55], v[168:171], v[176:179], v[52:55]
	s_setprio 0
	s_barrier
	s_add_i32 s78, 0, 0x18000
	s_add_i32 s79, 0, 0x1c000
	v_add_u32_e32 v68, s78, v153
	v_add_u32_e32 v168, s79, v153
	ds_read_b128 v[56:59], v68
	ds_read_b128 v[60:63], v68 offset:1024
	ds_read_b128 v[64:67], v68 offset:2048
	ds_read_b128 v[68:71], v68 offset:3072
	ds_read_b128 v[156:159], v168
	ds_read_b128 v[160:163], v168 offset:1024
	ds_read_b128 v[164:167], v168 offset:2048
	ds_read_b128 v[168:171], v168 offset:3072
	s_add_u32 s42, s42, 0x40000
	s_addc_u32 s43, s43, 0
	s_mov_b32 m0, s47
	v_lshl_add_u64 v[214:215], s[42:43], 0, v[184:185]
	ds_read_b128 v[172:175], v155 offset:32768
	ds_read_b128 v[176:179], v155 offset:33792
	ds_read_b128 v[180:183], v155 offset:34816
	ds_read_b128 v[190:193], v155 offset:35840
	ds_read_b128 v[194:197], v155 offset:36864
	ds_read_b128 v[198:201], v155 offset:37888
	ds_read_b128 v[202:205], v155 offset:38912
	ds_read_b128 v[206:209], v155 offset:39936
	global_load_lds_dwordx4 v[214:215], off
	v_lshl_add_u64 v[214:215], s[42:43], 0, v[144:145]
	s_mov_b32 m0, s48
	s_nop 0
	global_load_lds_dwordx4 v[214:215], off
	s_waitcnt vmcnt(8)
	s_waitcnt lgkmcnt(0)
	s_barrier
	s_setprio 1
	s_waitcnt lgkmcnt(0)
	v_mfma_f32_16x16x32_bf16 v[140:143], v[56:59], v[172:175], v[140:143]
	v_mfma_f32_16x16x32_bf16 v[136:139], v[64:67], v[172:175], v[136:139]
	v_mfma_f32_16x16x32_bf16 v[124:127], v[56:59], v[180:183], v[124:127]
	v_mfma_f32_16x16x32_bf16 v[120:123], v[64:67], v[180:183], v[120:123]
	v_mfma_f32_16x16x32_bf16 v[108:111], v[56:59], v[194:197], v[108:111]
	v_mfma_f32_16x16x32_bf16 v[104:107], v[64:67], v[194:197], v[104:107]
	v_mfma_f32_16x16x32_bf16 v[92:95], v[56:59], v[202:205], v[92:95]
	v_mfma_f32_16x16x32_bf16 v[88:91], v[64:67], v[202:205], v[88:91]
	v_mfma_f32_16x16x32_bf16 v[140:143], v[60:63], v[176:179], v[140:143]
	v_mfma_f32_16x16x32_bf16 v[136:139], v[68:71], v[176:179], v[136:139]
	v_mfma_f32_16x16x32_bf16 v[124:127], v[60:63], v[190:193], v[124:127]
	v_mfma_f32_16x16x32_bf16 v[120:123], v[68:71], v[190:193], v[120:123]
	v_mfma_f32_16x16x32_bf16 v[108:111], v[60:63], v[198:201], v[108:111]
	v_mfma_f32_16x16x32_bf16 v[104:107], v[68:71], v[198:201], v[104:107]
	v_mfma_f32_16x16x32_bf16 v[92:95], v[60:63], v[206:209], v[92:95]
	v_mfma_f32_16x16x32_bf16 v[88:91], v[68:71], v[206:209], v[88:91]
	s_setprio 0
	s_setprio 1
	v_mfma_f32_16x16x32_bf16 v[132:135], v[156:159], v[172:175], v[132:135]
	v_mfma_f32_16x16x32_bf16 v[128:131], v[164:167], v[172:175], v[128:131]
	v_mfma_f32_16x16x32_bf16 v[116:119], v[156:159], v[180:183], v[116:119]
	v_mfma_f32_16x16x32_bf16 v[112:115], v[164:167], v[180:183], v[112:115]
	v_mfma_f32_16x16x32_bf16 v[100:103], v[156:159], v[194:197], v[100:103]
	v_mfma_f32_16x16x32_bf16 v[96:99], v[164:167], v[194:197], v[96:99]
	v_mfma_f32_16x16x32_bf16 v[84:87], v[156:159], v[202:205], v[84:87]
	v_mfma_f32_16x16x32_bf16 v[80:83], v[164:167], v[202:205], v[80:83]
	v_mfma_f32_16x16x32_bf16 v[132:135], v[160:163], v[176:179], v[132:135]
	v_mfma_f32_16x16x32_bf16 v[128:131], v[168:171], v[176:179], v[128:131]
	v_mfma_f32_16x16x32_bf16 v[116:119], v[160:163], v[190:193], v[116:119]
	v_mfma_f32_16x16x32_bf16 v[112:115], v[168:171], v[190:193], v[112:115]
	v_mfma_f32_16x16x32_bf16 v[100:103], v[160:163], v[198:201], v[100:103]
	v_mfma_f32_16x16x32_bf16 v[96:99], v[168:171], v[198:201], v[96:99]
	v_mfma_f32_16x16x32_bf16 v[84:87], v[160:163], v[206:209], v[84:87]
	v_mfma_f32_16x16x32_bf16 v[80:83], v[168:171], v[206:209], v[80:83]
	s_setprio 0
	s_barrier
; #define PG8_STAGE(bufoff, gbase, voff) do { _Pragma("unroll") for (int _i = 0; _i < 2; ++_i) \
;         __builtin_amdgcn_global_load_lds((const unsigned*)((const char*)(gbase) + (voff)[_i]), (PG8_LAS unsigned*)(lds + (bufoff) + ldsw + _i * 8192), 16, 0, 0); } while (0)
; #define PG8_LDA(dst, b, h) do { _Pragma("unroll") for (int m = 0; m < 4; ++m) _Pragma("unroll") for (int k = 0; k < 2; ++k) dst[m][k] = *(const PG8_LAS bf16x8*)(lds + PG8_SA(b, h) + aoff + m * 2048 + k * 1024); } while (0)
; #define PG8_MMA(ai, bj, At, Bt) do { __builtin_amdgcn_s_setprio(1); _Pragma("unroll") for (int m = 0; m < 4; ++m) _Pragma("unroll") for (int n = 0; n < 2; ++n) _Pragma("unroll") for (int k = 0; k < 2; ++k) \
;         acc[ai][bj][m][n] = __builtin_amdgcn_mfma_f32_16x16x32_bf16(Bt[n][k], At[m][k], acc[ai][bj][m][n], 0, 0, 0); __builtin_amdgcn_s_setprio(0); } while (0)
; #define PG8_WAIT_V(n) asm volatile("s_waitcnt vmcnt(" #n ")" ::: "memory")
; #define PG8_WAIT_L(n) asm volatile("s_waitcnt lgkmcnt(" #n ")" ::: "memory")
; #define PG8_BAR __builtin_amdgcn_s_barrier()
; #define PG8_SCHED __builtin_amdgcn_sched_barrier(0)
; template <class Epi, class Sched, bool ALIGN_EPI = false, bool SP2 = false>
; __device__ __forceinline__ void gemm_phase(PG8_LAS unsigned char* lds, const Gemm g, const Sched& S, const Epi& E) {
;     ...
;         for (int t = 0; t < nt; t += 2) {
;             const bool last = (t == nt - 2);
;     ...
;             PG8_LDA(At, 1, 1); PG8_STAGE(PG8_SB(1, 0), b3, voffB); PG8_STAGE(PG8_SB(1, 1), b3 + hstep, voffB); PG8_STAGE(PG8_SA(1, 0), a3, voffA);
;             PG8_WAIT_V(8); PG8_WAIT_L(0); PG8_BAR; PG8_MMA(1, 0, At, B0); PG8_MMA(1, 1, At, B1); PG8_BAR; PG8_SCHED;
	s_add_i32 s42, s78, s44
	v_lshl_add_u64 v[150:151], v[150:151], 0, s[30:31]
	s_mov_b32 m0, s42
	ds_read_b128 v[172:175], v155 offset:49152
	ds_read_b128 v[176:179], v155 offset:50176
	ds_read_b128 v[180:183], v155 offset:51200
	ds_read_b128 v[190:193], v155 offset:52224
	ds_read_b128 v[194:197], v155 offset:53248
	ds_read_b128 v[198:201], v155 offset:54272
	ds_read_b128 v[202:205], v155 offset:55296
	ds_read_b128 v[206:209], v155 offset:56320
	global_load_lds_dwordx4 v[150:151], off
	s_add_i32 m0, s42, 0x2000
	s_add_u32 s36, s36, 0x40080
	v_lshl_add_u64 v[150:151], v[186:187], 0, s[30:31]
	s_addc_u32 s37, s37, 0
	s_add_i32 s42, s79, s44
	global_load_lds_dwordx4 v[150:151], off
	v_lshl_add_u64 v[150:151], s[36:37], 0, v[184:185]
	s_mov_b32 m0, s42
	s_nop 0
	global_load_lds_dwordx4 v[150:151], off
	v_lshl_add_u64 v[150:151], s[36:37], 0, v[144:145]
	s_add_i32 m0, s42, 0x2000
	s_nop 0
	global_load_lds_dwordx4 v[150:151], off
	v_lshl_add_u64 v[150:151], v[188:189], 0, s[30:31]
	s_mov_b32 m0, s49
	s_nop 0
	global_load_lds_dwordx4 v[150:151], off
	v_lshl_add_u64 v[150:151], v[210:211], 0, s[30:31]
	s_mov_b32 m0, s60
	s_nop 0
	global_load_lds_dwordx4 v[150:151], off
	s_waitcnt vmcnt(8)
	s_waitcnt lgkmcnt(0)
	s_barrier
	s_setprio 1
	s_waitcnt lgkmcnt(0)
	v_mfma_f32_16x16x32_bf16 v[76:79], v[56:59], v[172:175], v[76:79]
	v_mfma_f32_16x16x32_bf16 v[72:75], v[64:67], v[172:175], v[72:75]
	v_mfma_f32_16x16x32_bf16 v[44:47], v[56:59], v[180:183], v[44:47]
	v_mfma_f32_16x16x32_bf16 v[40:43], v[64:67], v[180:183], v[40:43]
	v_mfma_f32_16x16x32_bf16 v[28:31], v[56:59], v[194:197], v[28:31]
	v_mfma_f32_16x16x32_bf16 v[24:27], v[64:67], v[194:197], v[24:27]
	v_mfma_f32_16x16x32_bf16 v[12:15], v[56:59], v[202:205], v[12:15]
	v_mfma_f32_16x16x32_bf16 v[8:11], v[64:67], v[202:205], v[8:11]
	v_mfma_f32_16x16x32_bf16 v[76:79], v[60:63], v[176:179], v[76:79]
	v_mfma_f32_16x16x32_bf16 v[72:75], v[68:71], v[176:179], v[72:75]
	v_mfma_f32_16x16x32_bf16 v[44:47], v[60:63], v[190:193], v[44:47]
	v_mfma_f32_16x16x32_bf16 v[40:43], v[68:71], v[190:193], v[40:43]
	v_mfma_f32_16x16x32_bf16 v[28:31], v[60:63], v[198:201], v[28:31]
	v_mfma_f32_16x16x32_bf16 v[24:27], v[68:71], v[198:201], v[24:27]
	v_mfma_f32_16x16x32_bf16 v[12:15], v[60:63], v[206:209], v[12:15]
	v_mfma_f32_16x16x32_bf16 v[8:11], v[68:71], v[206:209], v[8:11]
	s_setprio 0
	s_setprio 1
	v_mfma_f32_16x16x32_bf16 v[48:51], v[156:159], v[172:175], v[48:51]
	v_mfma_f32_16x16x32_bf16 v[60:63], v[160:163], v[176:179], v[48:51]
	v_mfma_f32_16x16x32_bf16 v[48:51], v[164:167], v[172:175], v[52:55]
	v_mfma_f32_16x16x32_bf16 v[36:39], v[156:159], v[180:183], v[36:39]
	v_mfma_f32_16x16x32_bf16 v[32:35], v[164:167], v[180:183], v[32:35]
	v_mfma_f32_16x16x32_bf16 v[20:23], v[156:159], v[194:197], v[20:23]
	v_mfma_f32_16x16x32_bf16 v[16:19], v[164:167], v[194:197], v[16:19]
	v_mfma_f32_16x16x32_bf16 v[4:7], v[156:159], v[202:205], v[4:7]
	v_mfma_f32_16x16x32_bf16 v[0:3], v[164:167], v[202:205], v[0:3]
	v_mfma_f32_16x16x32_bf16 v[56:59], v[168:171], v[176:179], v[48:51]
	v_mfma_f32_16x16x32_bf16 v[36:39], v[160:163], v[190:193], v[36:39]
	v_mfma_f32_16x16x32_bf16 v[32:35], v[168:171], v[190:193], v[32:35]
	v_mfma_f32_16x16x32_bf16 v[20:23], v[160:163], v[198:201], v[20:23]
	v_mfma_f32_16x16x32_bf16 v[16:19], v[168:171], v[198:201], v[16:19]
	v_mfma_f32_16x16x32_bf16 v[4:7], v[160:163], v[206:209], v[4:7]
	v_mfma_f32_16x16x32_bf16 v[0:3], v[168:171], v[206:209], v[0:3]
	s_setprio 0
	s_barrier
	s_add_i32 s77, s77, 2
	s_add_u32 s24, s24, 0x100
	s_addc_u32 s25, s25, 0
	s_add_u32 s73, s73, 0x100
	s_addc_u32 s76, s76, 0
	s_cmp_gt_u32 s77, 13
	s_cbranch_scc0 .LBB0_374
	s_branch .Lgzero1_done

; #define PG8_BAR __builtin_amdgcn_s_barrier()
; template <class Epi, class Sched, bool ALIGN_EPI = false, bool SP2 = false>
; __device__ __forceinline__ void gemm_phase(PG8_LAS unsigned char* lds, const Gemm g, const Sched& S, const Epi& E) {
;     ...
;         if constexpr (ALIGN_EPI) { if (wr == 0) PG8_BAR; }
;         if constexpr (!Epi::AFTER_DRAIN) { E(acc, cur, wr, wc, fr, fq); S.done(cur); }
.Lgzero1_done:
	s_and_b64 vcc, exec, s[14:15]
	s_cbranch_vccz .LBB0_377
	s_barrier

;     __host__ __device__ bool next(int i, Unit& u) const { Unit m; if (!S.next(i >> 1, m)) return false; u.pm = m.pm; u.pn = m.pn + 4 * (i & 1); return true; }
;     __host__ __device__ bool next(int i, Unit& u) const { Unit m; if (!S.next(i >> 1, m)) return false; u.pm = m.pm + (i & 1) * dpm; u.pn = m.pn + (i & 1) * dpn; return true; }
; #define PG8_STAGE(bufoff, gbase, voff) do { _Pragma("unroll") for (int _i = 0; _i < 2; ++_i) \
;         __builtin_amdgcn_global_load_lds((const unsigned*)((const char*)(gbase) + (voff)[_i]), (PG8_LAS unsigned*)(lds + (bufoff) + ldsw + _i * 8192), 16, 0, 0); } while (0)
; #define PG8_LDA(dst, b, h) do { _Pragma("unroll") for (int m = 0; m < 4; ++m) _Pragma("unroll") for (int k = 0; k < 2; ++k) dst[m][k] = *(const PG8_LAS bf16x8*)(lds + PG8_SA(b, h) + aoff + m * 2048 + k * 1024); } while (0)
; #define PG8_WAIT_V(n) asm volatile("s_waitcnt vmcnt(" #n ")" ::: "memory")
; #define PG8_WAIT_L(n) asm volatile("s_waitcnt lgkmcnt(" #n ")" ::: "memory")
; template <class Epi, class Sched, bool ALIGN_EPI = false, bool SP2 = false>
; __device__ __forceinline__ void gemm_phase(PG8_LAS unsigned char* lds, const Gemm g, const Sched& S, const Epi& E) {
;     ...
;         const bool has_next = S.next(ui + 1, nxt);
;         const char* nA = has_next ? (const char*)g.A + (size_t)nxt.pm * tstep : cA; const char* nB = has_next ? (const char*)g.Bt + (size_t)nxt.pn * tstep : cB;
;         for (int t = 0; t < nt; t += 2) {
;             const bool last = (t == nt - 2);
;             const char* a1 = cA + (size_t)(t + 1) * kstep;
;             const char* a2 = last ? nA : cA + (size_t)(t + 2) * kstep; const char* b2 = last ? nB : cB + (size_t)(t + 2) * kstep;
;             const char* a3 = a2 + kstep; const char* b3 = b2 + kstep;
;             if (last && has_next) S.a_ready(nxt);
;             if constexpr (SP2) {
;             PG8_LDB(B0, 0, 0); PG8_LDB(B1, 0, 1); PG8_SCHED; PG8_LDA(At, 0, 0); PG8_STAGE(PG8_SA(1, 1), a1 + hstep, voffA);
;             PG8_WAIT_V(8); PG8_WAIT_L(0); PG8_BAR; PG8_MMA(0, 0, At, B0); PG8_MMA(0, 1, At, B1); PG8_BAR; PG8_SCHED;
;             PG8_LDA(At, 0, 1); PG8_STAGE(PG8_SB(0, 0), b2, voffB); PG8_STAGE(PG8_SB(0, 1), b2 + hstep, voffB); PG8_STAGE(PG8_SA(0, 0), a2, voffA);
;             PG8_WAIT_V(8); PG8_WAIT_L(0); PG8_BAR; PG8_MMA(1, 0, At, B0); PG8_MMA(1, 1, At, B1); PG8_BAR; PG8_SCHED;
.LBB0_394:
	s_ashr_i32 s15, s14, 31
	s_lshl_b64 s[18:19], s[14:15], 18
	s_add_u32 s18, s91, s18
	s_addc_u32 s19, s81, s19
	s_and_b64 s[20:21], s[6:7], exec
	s_cselect_b32 s15, s19, s23
	s_cselect_b32 s69, s18, s22
	s_ashr_i32 s17, s16, 31
	s_lshl_b64 s[20:21], s[16:17], 18
	s_add_u32 s20, s28, s20
	s_addc_u32 s21, s29, s21
	s_and_b64 s[36:37], s[6:7], exec
	s_cselect_b32 s17, s21, s25
	s_cselect_b32 s70, s20, s24
	s_add_u32 s22, s22, 0x20080
	s_addc_u32 s23, s23, 0
	s_add_u32 s71, s24, 0x100
	s_addc_u32 s72, s25, 0
	s_mov_b32 s73, -2
	s_add_u32 s24, s22, 0xfffe0080
	s_addc_u32 s25, s23, -1
	s_add_i32 s76, 0, 0x10000
	s_cmp_eq_u32 s73, 4
	s_cselect_b32 s37, s15, s25
	s_cselect_b32 s36, s69, s24
	s_cselect_b32 s25, s17, s72
	s_cselect_b32 s24, s70, s71
	s_add_i32 s78, 0, 0x14000
	v_add_u32_e32 v140, s76, v224
	v_add_u32_e32 v156, s78, v224
	ds_read_b128 v[128:131], v140
	ds_read_b128 v[132:135], v140 offset:1024
	ds_read_b128 v[136:139], v140 offset:2048
	ds_read_b128 v[140:143], v140 offset:3072
	ds_read_b128 v[144:147], v156
	ds_read_b128 v[148:151], v156 offset:1024
	ds_read_b128 v[152:155], v156 offset:2048
	ds_read_b128 v[156:159], v156 offset:3072
	v_lshl_add_u64 v[186:187], s[22:23], 0, v[192:193]
	s_add_i32 m0, s43, 0xc000
	ds_read_b128 v[160:163], v228
	ds_read_b128 v[164:167], v228 offset:1024
	ds_read_b128 v[168:171], v228 offset:2048
	ds_read_b128 v[172:175], v228 offset:3072
	ds_read_b128 v[176:179], v228 offset:4096
	ds_read_b128 v[180:183], v228 offset:5120
	ds_read_b128 v[196:199], v228 offset:6144
	ds_read_b128 v[200:203], v228 offset:7168
	global_load_lds_dwordx4 v[186:187], off
	v_lshl_add_u64 v[186:187], s[22:23], 0, v[194:195]
	s_add_i32 m0, s43, 0xe000
	s_nop 0
	global_load_lds_dwordx4 v[186:187], off
	s_waitcnt vmcnt(8)
	s_waitcnt lgkmcnt(0)
	s_barrier
	s_setprio 1
	s_waitcnt lgkmcnt(0)
	v_mfma_f32_16x16x32_bf16 v[124:127], v[128:131], v[160:163], 0
	v_mfma_f32_16x16x32_bf16 v[120:123], v[136:139], v[160:163], 0
	v_mfma_f32_16x16x32_bf16 v[108:111], v[128:131], v[168:171], 0
	v_mfma_f32_16x16x32_bf16 v[104:107], v[136:139], v[168:171], 0
	v_mfma_f32_16x16x32_bf16 v[96:99], v[128:131], v[176:179], 0
	v_mfma_f32_16x16x32_bf16 v[88:91], v[136:139], v[176:179], 0
	v_mfma_f32_16x16x32_bf16 v[80:83], v[128:131], v[196:199], 0
	v_mfma_f32_16x16x32_bf16 v[72:75], v[136:139], v[196:199], 0
	v_mfma_f32_16x16x32_bf16 v[124:127], v[132:135], v[164:167], v[124:127]
	v_mfma_f32_16x16x32_bf16 v[120:123], v[140:143], v[164:167], v[120:123]
	v_mfma_f32_16x16x32_bf16 v[108:111], v[132:135], v[172:175], v[108:111]
	v_mfma_f32_16x16x32_bf16 v[104:107], v[140:143], v[172:175], v[104:107]
	v_mfma_f32_16x16x32_bf16 v[96:99], v[132:135], v[180:183], v[96:99]
	v_mfma_f32_16x16x32_bf16 v[88:91], v[140:143], v[180:183], v[88:91]
	v_mfma_f32_16x16x32_bf16 v[80:83], v[132:135], v[200:203], v[80:83]
	v_mfma_f32_16x16x32_bf16 v[72:75], v[140:143], v[200:203], v[72:75]
	s_setprio 0
	s_setprio 1
	v_mfma_f32_16x16x32_bf16 v[116:119], v[144:147], v[160:163], 0
	v_mfma_f32_16x16x32_bf16 v[112:115], v[152:155], v[160:163], 0
	v_mfma_f32_16x16x32_bf16 v[100:103], v[144:147], v[168:171], 0
	v_mfma_f32_16x16x32_bf16 v[92:95], v[152:155], v[168:171], 0
	v_mfma_f32_16x16x32_bf16 v[84:87], v[144:147], v[176:179], 0
	v_mfma_f32_16x16x32_bf16 v[76:79], v[152:155], v[176:179], 0
	v_mfma_f32_16x16x32_bf16 v[68:71], v[144:147], v[196:199], 0
	v_mfma_f32_16x16x32_bf16 v[64:67], v[152:155], v[196:199], 0
	v_mfma_f32_16x16x32_bf16 v[116:119], v[148:151], v[164:167], v[116:119]
	v_mfma_f32_16x16x32_bf16 v[112:115], v[156:159], v[164:167], v[112:115]
	v_mfma_f32_16x16x32_bf16 v[100:103], v[148:151], v[172:175], v[100:103]
	v_mfma_f32_16x16x32_bf16 v[92:95], v[156:159], v[172:175], v[92:95]
	v_mfma_f32_16x16x32_bf16 v[84:87], v[148:151], v[180:183], v[84:87]
	v_mfma_f32_16x16x32_bf16 v[76:79], v[156:159], v[180:183], v[76:79]
	v_mfma_f32_16x16x32_bf16 v[68:71], v[148:151], v[200:203], v[68:71]
	v_mfma_f32_16x16x32_bf16 v[64:67], v[156:159], v[200:203], v[64:67]
	s_setprio 0
	s_barrier
	s_add_i32 s76, s76, s42
	v_lshl_add_u64 v[186:187], s[24:25], 0, v[184:185]
	s_mov_b32 m0, s76
	ds_read_b128 v[160:163], v228 offset:16384
	ds_read_b128 v[164:167], v228 offset:17408
	ds_read_b128 v[168:171], v228 offset:18432
	ds_read_b128 v[172:175], v228 offset:19456
	ds_read_b128 v[176:179], v228 offset:20480
	ds_read_b128 v[180:183], v228 offset:21504
	ds_read_b128 v[196:199], v228 offset:22528
	ds_read_b128 v[200:203], v228 offset:23552
	global_load_lds_dwordx4 v[186:187], off
	s_add_i32 m0, s76, 0x2000
	s_add_u32 s76, s24, 0x20000
	v_lshl_add_u64 v[188:189], s[24:25], 0, v[190:191]
	s_addc_u32 s77, s25, 0
	s_add_i32 s78, s78, s42
	global_load_lds_dwordx4 v[188:189], off
	v_lshl_add_u64 v[204:205], s[76:77], 0, v[184:185]
	s_mov_b32 m0, s78
	v_lshl_add_u64 v[206:207], s[36:37], 0, v[190:191]
	global_load_lds_dwordx4 v[204:205], off
	v_lshl_add_u64 v[204:205], s[76:77], 0, v[190:191]
	s_add_i32 m0, s78, 0x2000
	s_nop 0
	global_load_lds_dwordx4 v[204:205], off
	v_lshl_add_u64 v[204:205], s[36:37], 0, v[184:185]
	s_mov_b32 m0, s43
	s_nop 0
	global_load_lds_dwordx4 v[204:205], off
	s_mov_b32 m0, s44
	s_nop 0
	global_load_lds_dwordx4 v[206:207], off
	s_waitcnt vmcnt(8)
	s_waitcnt lgkmcnt(0)
	s_barrier
; #define PG8_STAGE(bufoff, gbase, voff) do { _Pragma("unroll") for (int _i = 0; _i < 2; ++_i) \
;         __builtin_amdgcn_global_load_lds((const unsigned*)((const char*)(gbase) + (voff)[_i]), (PG8_LAS unsigned*)(lds + (bufoff) + ldsw + _i * 8192), 16, 0, 0); } while (0)
; #define PG8_LDA(dst, b, h) do { _Pragma("unroll") for (int m = 0; m < 4; ++m) _Pragma("unroll") for (int k = 0; k < 2; ++k) dst[m][k] = *(const PG8_LAS bf16x8*)(lds + PG8_SA(b, h) + aoff + m * 2048 + k * 1024); } while (0)
; #define PG8_LDB(dst, b, h) do { _Pragma("unroll") for (int n = 0; n < 2; ++n) _Pragma("unroll") for (int k = 0; k < 2; ++k) dst[n][k] = *(const PG8_LAS bf16x8*)(lds + PG8_SB(b, h) + boff + n * 2048 + k * 1024); } while (0)
; #define PG8_MMA(ai, bj, At, Bt) do { __builtin_amdgcn_s_setprio(1); _Pragma("unroll") for (int m = 0; m < 4; ++m) _Pragma("unroll") for (int n = 0; n < 2; ++n) _Pragma("unroll") for (int k = 0; k < 2; ++k) \
;         acc[ai][bj][m][n] = __builtin_amdgcn_mfma_f32_16x16x32_bf16(Bt[n][k], At[m][k], acc[ai][bj][m][n], 0, 0, 0); __builtin_amdgcn_s_setprio(0); } while (0)
; #define PG8_WAIT_V(n) asm volatile("s_waitcnt vmcnt(" #n ")" ::: "memory")
; #define PG8_WAIT_L(n) asm volatile("s_waitcnt lgkmcnt(" #n ")" ::: "memory")
; #define PG8_BAR __builtin_amdgcn_s_barrier()
; #define PG8_SCHED __builtin_amdgcn_sched_barrier(0)
; template <class Epi, class Sched, bool ALIGN_EPI = false, bool SP2 = false>
; __device__ __forceinline__ void gemm_phase(PG8_LAS unsigned char* lds, const Gemm g, const Sched& S, const Epi& E) {
;     ...
;             PG8_WAIT_V(8); PG8_WAIT_L(0); PG8_BAR; PG8_MMA(1, 0, At, B0); PG8_MMA(1, 1, At, B1); PG8_BAR; PG8_SCHED;
;             PG8_LDB(B0, 1, 0); PG8_LDB(B1, 1, 1); PG8_SCHED; PG8_LDA(At, 1, 0); PG8_STAGE(PG8_SA(0, 1), a2 + hstep, voffA);
;             PG8_WAIT_V(8); PG8_WAIT_L(0); PG8_BAR; PG8_MMA(0, 0, At, B0); PG8_MMA(0, 1, At, B1); PG8_BAR; PG8_SCHED;
	s_setprio 1
	s_waitcnt lgkmcnt(0)
	v_mfma_f32_16x16x32_bf16 v[60:63], v[128:131], v[160:163], 0
	v_mfma_f32_16x16x32_bf16 v[56:59], v[136:139], v[160:163], 0
	v_mfma_f32_16x16x32_bf16 v[48:51], v[128:131], v[168:171], 0
	v_mfma_f32_16x16x32_bf16 v[40:43], v[136:139], v[168:171], 0
	v_mfma_f32_16x16x32_bf16 v[32:35], v[128:131], v[176:179], 0
	v_mfma_f32_16x16x32_bf16 v[24:27], v[136:139], v[176:179], 0
	v_mfma_f32_16x16x32_bf16 v[16:19], v[128:131], v[196:199], 0
	v_mfma_f32_16x16x32_bf16 v[8:11], v[136:139], v[196:199], 0
	v_mfma_f32_16x16x32_bf16 v[60:63], v[132:135], v[164:167], v[60:63]
	v_mfma_f32_16x16x32_bf16 v[56:59], v[140:143], v[164:167], v[56:59]
	v_mfma_f32_16x16x32_bf16 v[48:51], v[132:135], v[172:175], v[48:51]
	v_mfma_f32_16x16x32_bf16 v[40:43], v[140:143], v[172:175], v[40:43]
	v_mfma_f32_16x16x32_bf16 v[32:35], v[132:135], v[180:183], v[32:35]
	v_mfma_f32_16x16x32_bf16 v[24:27], v[140:143], v[180:183], v[24:27]
	v_mfma_f32_16x16x32_bf16 v[16:19], v[132:135], v[200:203], v[16:19]
	v_mfma_f32_16x16x32_bf16 v[8:11], v[140:143], v[200:203], v[8:11]
	s_setprio 0
	s_setprio 1
	v_mfma_f32_16x16x32_bf16 v[52:55], v[144:147], v[160:163], 0
	v_mfma_f32_16x16x32_bf16 v[44:47], v[152:155], v[160:163], 0
	v_mfma_f32_16x16x32_bf16 v[36:39], v[144:147], v[168:171], 0
	v_mfma_f32_16x16x32_bf16 v[28:31], v[152:155], v[168:171], 0
	v_mfma_f32_16x16x32_bf16 v[20:23], v[144:147], v[176:179], 0
	v_mfma_f32_16x16x32_bf16 v[12:15], v[152:155], v[176:179], 0
	v_mfma_f32_16x16x32_bf16 v[4:7], v[144:147], v[196:199], 0
	v_mfma_f32_16x16x32_bf16 v[0:3], v[152:155], v[196:199], 0
	v_mfma_f32_16x16x32_bf16 v[52:55], v[148:151], v[164:167], v[52:55]
	v_mfma_f32_16x16x32_bf16 v[44:47], v[156:159], v[164:167], v[44:47]
	v_mfma_f32_16x16x32_bf16 v[36:39], v[148:151], v[172:175], v[36:39]
	v_mfma_f32_16x16x32_bf16 v[28:31], v[156:159], v[172:175], v[28:31]
	v_mfma_f32_16x16x32_bf16 v[20:23], v[148:151], v[180:183], v[20:23]
	v_mfma_f32_16x16x32_bf16 v[12:15], v[156:159], v[180:183], v[12:15]
	v_mfma_f32_16x16x32_bf16 v[4:7], v[148:151], v[200:203], v[4:7]
	v_mfma_f32_16x16x32_bf16 v[0:3], v[156:159], v[200:203], v[0:3]
	s_setprio 0
	s_barrier
	s_add_i32 s76, 0, 0x18000
	s_add_i32 s77, 0, 0x1c000
	v_add_u32_e32 v140, s76, v224
	v_add_u32_e32 v156, s77, v224
	ds_read_b128 v[128:131], v140
	ds_read_b128 v[132:135], v140 offset:1024
	ds_read_b128 v[136:139], v140 offset:2048
	ds_read_b128 v[140:143], v140 offset:3072
	ds_read_b128 v[144:147], v156
	ds_read_b128 v[148:151], v156 offset:1024
	ds_read_b128 v[152:155], v156 offset:2048
	ds_read_b128 v[156:159], v156 offset:3072
	s_add_u32 s36, s36, 0x20000
	s_addc_u32 s37, s37, 0
	s_mov_b32 m0, s45
	v_lshl_add_u64 v[208:209], s[36:37], 0, v[184:185]
	ds_read_b128 v[160:163], v228 offset:32768
	ds_read_b128 v[164:167], v228 offset:33792
	ds_read_b128 v[168:171], v228 offset:34816
	ds_read_b128 v[172:175], v228 offset:35840
	ds_read_b128 v[176:179], v228 offset:36864
	ds_read_b128 v[180:183], v228 offset:37888
	ds_read_b128 v[196:199], v228 offset:38912
	ds_read_b128 v[200:203], v228 offset:39936
	global_load_lds_dwordx4 v[208:209], off
	v_lshl_add_u64 v[208:209], s[36:37], 0, v[190:191]
	s_mov_b32 m0, s46
	s_nop 0
	global_load_lds_dwordx4 v[208:209], off
	s_waitcnt vmcnt(8)
	s_waitcnt lgkmcnt(0)
	s_barrier
	s_setprio 1
	s_waitcnt lgkmcnt(0)
	v_mfma_f32_16x16x32_bf16 v[124:127], v[128:131], v[160:163], v[124:127]
	v_mfma_f32_16x16x32_bf16 v[120:123], v[136:139], v[160:163], v[120:123]
	v_mfma_f32_16x16x32_bf16 v[108:111], v[128:131], v[168:171], v[108:111]
	v_mfma_f32_16x16x32_bf16 v[104:107], v[136:139], v[168:171], v[104:107]
	v_mfma_f32_16x16x32_bf16 v[96:99], v[128:131], v[176:179], v[96:99]
	v_mfma_f32_16x16x32_bf16 v[88:91], v[136:139], v[176:179], v[88:91]
	v_mfma_f32_16x16x32_bf16 v[80:83], v[128:131], v[196:199], v[80:83]
	v_mfma_f32_16x16x32_bf16 v[72:75], v[136:139], v[196:199], v[72:75]
	v_mfma_f32_16x16x32_bf16 v[124:127], v[132:135], v[164:167], v[124:127]
	v_mfma_f32_16x16x32_bf16 v[120:123], v[140:143], v[164:167], v[120:123]
	v_mfma_f32_16x16x32_bf16 v[108:111], v[132:135], v[172:175], v[108:111]
	v_mfma_f32_16x16x32_bf16 v[104:107], v[140:143], v[172:175], v[104:107]
	v_mfma_f32_16x16x32_bf16 v[96:99], v[132:135], v[180:183], v[96:99]
	v_mfma_f32_16x16x32_bf16 v[88:91], v[140:143], v[180:183], v[88:91]
	v_mfma_f32_16x16x32_bf16 v[80:83], v[132:135], v[200:203], v[80:83]
	v_mfma_f32_16x16x32_bf16 v[72:75], v[140:143], v[200:203], v[72:75]
	s_setprio 0
	s_setprio 1
	v_mfma_f32_16x16x32_bf16 v[116:119], v[144:147], v[160:163], v[116:119]
	v_mfma_f32_16x16x32_bf16 v[112:115], v[152:155], v[160:163], v[112:115]
	v_mfma_f32_16x16x32_bf16 v[100:103], v[144:147], v[168:171], v[100:103]
	v_mfma_f32_16x16x32_bf16 v[92:95], v[152:155], v[168:171], v[92:95]
	v_mfma_f32_16x16x32_bf16 v[84:87], v[144:147], v[176:179], v[84:87]
	v_mfma_f32_16x16x32_bf16 v[76:79], v[152:155], v[176:179], v[76:79]
	v_mfma_f32_16x16x32_bf16 v[68:71], v[144:147], v[196:199], v[68:71]
	v_mfma_f32_16x16x32_bf16 v[64:67], v[152:155], v[196:199], v[64:67]
	v_mfma_f32_16x16x32_bf16 v[116:119], v[148:151], v[164:167], v[116:119]
	v_mfma_f32_16x16x32_bf16 v[112:115], v[156:159], v[164:167], v[112:115]
	v_mfma_f32_16x16x32_bf16 v[100:103], v[148:151], v[172:175], v[100:103]
	v_mfma_f32_16x16x32_bf16 v[92:95], v[156:159], v[172:175], v[92:95]
	v_mfma_f32_16x16x32_bf16 v[84:87], v[148:151], v[180:183], v[84:87]
	v_mfma_f32_16x16x32_bf16 v[76:79], v[156:159], v[180:183], v[76:79]
	v_mfma_f32_16x16x32_bf16 v[68:71], v[148:151], v[200:203], v[68:71]
	v_mfma_f32_16x16x32_bf16 v[64:67], v[156:159], v[200:203], v[64:67]
	s_setprio 0
	s_barrier
; #define PG8_STAGE(bufoff, gbase, voff) do { _Pragma("unroll") for (int _i = 0; _i < 2; ++_i) \
;         __builtin_amdgcn_global_load_lds((const unsigned*)((const char*)(gbase) + (voff)[_i]), (PG8_LAS unsigned*)(lds + (bufoff) + ldsw + _i * 8192), 16, 0, 0); } while (0)
; #define PG8_LDA(dst, b, h) do { _Pragma("unroll") for (int m = 0; m < 4; ++m) _Pragma("unroll") for (int k = 0; k < 2; ++k) dst[m][k] = *(const PG8_LAS bf16x8*)(lds + PG8_SA(b, h) + aoff + m * 2048 + k * 1024); } while (0)
; #define PG8_MMA(ai, bj, At, Bt) do { __builtin_amdgcn_s_setprio(1); _Pragma("unroll") for (int m = 0; m < 4; ++m) _Pragma("unroll") for (int n = 0; n < 2; ++n) _Pragma("unroll") for (int k = 0; k < 2; ++k) \
;         acc[ai][bj][m][n] = __builtin_amdgcn_mfma_f32_16x16x32_bf16(Bt[n][k], At[m][k], acc[ai][bj][m][n], 0, 0, 0); __builtin_amdgcn_s_setprio(0); } while (0)
; #define PG8_WAIT_V(n) asm volatile("s_waitcnt vmcnt(" #n ")" ::: "memory")
; #define PG8_WAIT_L(n) asm volatile("s_waitcnt lgkmcnt(" #n ")" ::: "memory")
; #define PG8_BAR __builtin_amdgcn_s_barrier()
; #define PG8_SCHED __builtin_amdgcn_sched_barrier(0)
; template <class Epi, class Sched, bool ALIGN_EPI = false, bool SP2 = false>
; __device__ __forceinline__ void gemm_phase(PG8_LAS unsigned char* lds, const Gemm g, const Sched& S, const Epi& E) {
;     ...
;         for (int t = 0; t < nt; t += 2) {
;             const bool last = (t == nt - 2);
;     ...
;             PG8_LDA(At, 1, 1); PG8_STAGE(PG8_SB(1, 0), b3, voffB); PG8_STAGE(PG8_SB(1, 1), b3 + hstep, voffB); PG8_STAGE(PG8_SA(1, 0), a3, voffA);
;             PG8_WAIT_V(8); PG8_WAIT_L(0); PG8_BAR; PG8_MMA(1, 0, At, B0); PG8_MMA(1, 1, At, B1); PG8_BAR; PG8_SCHED;
	s_add_i32 s36, s76, s42
	v_lshl_add_u64 v[186:187], v[186:187], 0, s[30:31]
	s_mov_b32 m0, s36
	ds_read_b128 v[160:163], v228 offset:49152
	ds_read_b128 v[164:167], v228 offset:50176
	ds_read_b128 v[168:171], v228 offset:51200
	ds_read_b128 v[172:175], v228 offset:52224
	ds_read_b128 v[176:179], v228 offset:53248
	ds_read_b128 v[180:183], v228 offset:54272
	ds_read_b128 v[196:199], v228 offset:55296
	ds_read_b128 v[200:203], v228 offset:56320
	global_load_lds_dwordx4 v[186:187], off
	s_add_i32 m0, s36, 0x2000
	s_add_u32 s24, s24, 0x20080
	v_lshl_add_u64 v[186:187], v[188:189], 0, s[30:31]
	s_addc_u32 s25, s25, 0
	s_add_i32 s36, s77, s42
	global_load_lds_dwordx4 v[186:187], off
	v_lshl_add_u64 v[186:187], s[24:25], 0, v[184:185]
	s_mov_b32 m0, s36
	s_nop 0
	global_load_lds_dwordx4 v[186:187], off
	v_lshl_add_u64 v[186:187], s[24:25], 0, v[190:191]
	s_add_i32 m0, s36, 0x2000
	s_nop 0
	global_load_lds_dwordx4 v[186:187], off
	v_lshl_add_u64 v[186:187], v[204:205], 0, s[30:31]
	s_mov_b32 m0, s47
	s_nop 0
	global_load_lds_dwordx4 v[186:187], off
	v_lshl_add_u64 v[186:187], v[206:207], 0, s[30:31]
	s_mov_b32 m0, s48
	s_nop 0
	global_load_lds_dwordx4 v[186:187], off
	s_waitcnt vmcnt(8)
	s_waitcnt lgkmcnt(0)
	s_barrier
	s_setprio 1
	s_waitcnt lgkmcnt(0)
	v_mfma_f32_16x16x32_bf16 v[60:63], v[128:131], v[160:163], v[60:63]
	v_mfma_f32_16x16x32_bf16 v[56:59], v[136:139], v[160:163], v[56:59]
	v_mfma_f32_16x16x32_bf16 v[48:51], v[128:131], v[168:171], v[48:51]
	v_mfma_f32_16x16x32_bf16 v[40:43], v[136:139], v[168:171], v[40:43]
	v_mfma_f32_16x16x32_bf16 v[32:35], v[128:131], v[176:179], v[32:35]
	v_mfma_f32_16x16x32_bf16 v[24:27], v[136:139], v[176:179], v[24:27]
	v_mfma_f32_16x16x32_bf16 v[16:19], v[128:131], v[196:199], v[16:19]
	v_mfma_f32_16x16x32_bf16 v[8:11], v[136:139], v[196:199], v[8:11]
	v_mfma_f32_16x16x32_bf16 v[60:63], v[132:135], v[164:167], v[60:63]
	v_mfma_f32_16x16x32_bf16 v[56:59], v[140:143], v[164:167], v[56:59]
	v_mfma_f32_16x16x32_bf16 v[48:51], v[132:135], v[172:175], v[48:51]
	v_mfma_f32_16x16x32_bf16 v[40:43], v[140:143], v[172:175], v[40:43]
	v_mfma_f32_16x16x32_bf16 v[32:35], v[132:135], v[180:183], v[32:35]
	v_mfma_f32_16x16x32_bf16 v[24:27], v[140:143], v[180:183], v[24:27]
	v_mfma_f32_16x16x32_bf16 v[16:19], v[132:135], v[200:203], v[16:19]
	v_mfma_f32_16x16x32_bf16 v[8:11], v[140:143], v[200:203], v[8:11]
	s_setprio 0
	s_setprio 1
	v_mfma_f32_16x16x32_bf16 v[52:55], v[144:147], v[160:163], v[52:55]
	v_mfma_f32_16x16x32_bf16 v[44:47], v[152:155], v[160:163], v[44:47]
	v_mfma_f32_16x16x32_bf16 v[36:39], v[144:147], v[168:171], v[36:39]
	v_mfma_f32_16x16x32_bf16 v[28:31], v[152:155], v[168:171], v[28:31]
	v_mfma_f32_16x16x32_bf16 v[20:23], v[144:147], v[176:179], v[20:23]
	v_mfma_f32_16x16x32_bf16 v[12:15], v[152:155], v[176:179], v[12:15]
	v_mfma_f32_16x16x32_bf16 v[4:7], v[144:147], v[196:199], v[4:7]
	v_mfma_f32_16x16x32_bf16 v[0:3], v[152:155], v[196:199], v[0:3]
	v_mfma_f32_16x16x32_bf16 v[52:55], v[148:151], v[164:167], v[52:55]
	v_mfma_f32_16x16x32_bf16 v[44:47], v[156:159], v[164:167], v[44:47]
	v_mfma_f32_16x16x32_bf16 v[36:39], v[148:151], v[172:175], v[36:39]
	v_mfma_f32_16x16x32_bf16 v[28:31], v[156:159], v[172:175], v[28:31]
	v_mfma_f32_16x16x32_bf16 v[20:23], v[148:151], v[180:183], v[20:23]
	v_mfma_f32_16x16x32_bf16 v[12:15], v[156:159], v[180:183], v[12:15]
	v_mfma_f32_16x16x32_bf16 v[4:7], v[148:151], v[200:203], v[4:7]
	v_mfma_f32_16x16x32_bf16 v[0:3], v[156:159], v[200:203], v[0:3]
	s_setprio 0
	s_barrier
	s_add_i32 s73, s73, 2
	s_add_u32 s22, s22, 0x100
	s_addc_u32 s23, s23, 0
	s_add_u32 s71, s71, 0x100
	s_addc_u32 s72, s72, 0
	s_cmp_gt_u32 s73, 5
	s_cbranch_scc0 .LBB0_395
	s_branch .Lgzero2_done

;     __host__ __device__ bool next(int i, Unit& u) const { Unit m; if (!S.next(i >> 1, m)) return false; u.pm = m.pm; u.pn = m.pn + 4 * (i & 1); return true; }
;     __host__ __device__ bool next(int i, Unit& u) const { Unit m; if (!S.next(i >> 1, m)) return false; u.pm = m.pm + (i & 1) * dpm; u.pn = m.pn + (i & 1) * dpn; return true; }
; #define PG8_STAGE(bufoff, gbase, voff) do { _Pragma("unroll") for (int _i = 0; _i < 2; ++_i) \
;         __builtin_amdgcn_global_load_lds((const unsigned*)((const char*)(gbase) + (voff)[_i]), (PG8_LAS unsigned*)(lds + (bufoff) + ldsw + _i * 8192), 16, 0, 0); } while (0)
; #define PG8_LDA(dst, b, h) do { _Pragma("unroll") for (int m = 0; m < 4; ++m) _Pragma("unroll") for (int k = 0; k < 2; ++k) dst[m][k] = *(const PG8_LAS bf16x8*)(lds + PG8_SA(b, h) + aoff + m * 2048 + k * 1024); } while (0)
; #define PG8_WAIT_V(n) asm volatile("s_waitcnt vmcnt(" #n ")" ::: "memory")
; #define PG8_WAIT_L(n) asm volatile("s_waitcnt lgkmcnt(" #n ")" ::: "memory")
; template <class Epi, class Sched, bool ALIGN_EPI = false, bool SP2 = false>
; __device__ __forceinline__ void gemm_phase(PG8_LAS unsigned char* lds, const Gemm g, const Sched& S, const Epi& E) {
;     ...
;         const bool has_next = S.next(ui + 1, nxt);
;         const char* nA = has_next ? (const char*)g.A + (size_t)nxt.pm * tstep : cA; const char* nB = has_next ? (const char*)g.Bt + (size_t)nxt.pn * tstep : cB;
;         for (int t = 0; t < nt; t += 2) {
;             const bool last = (t == nt - 2);
;             const char* a1 = cA + (size_t)(t + 1) * kstep;
;             const char* a2 = last ? nA : cA + (size_t)(t + 2) * kstep; const char* b2 = last ? nB : cB + (size_t)(t + 2) * kstep;
;             const char* a3 = a2 + kstep; const char* b3 = b2 + kstep;
;             if (last && has_next) S.a_ready(nxt);
;             if constexpr (SP2) {
;             PG8_LDB(B0, 0, 0); PG8_LDB(B1, 0, 1); PG8_SCHED; PG8_LDA(At, 0, 0); PG8_STAGE(PG8_SA(1, 1), a1 + hstep, voffA);
;             PG8_WAIT_V(8); PG8_WAIT_L(0); PG8_BAR; PG8_MMA(0, 0, At, B0); PG8_MMA(0, 1, At, B1); PG8_BAR; PG8_SCHED;
;             PG8_LDA(At, 0, 1); PG8_STAGE(PG8_SB(0, 0), b2, voffB); PG8_STAGE(PG8_SB(0, 1), b2 + hstep, voffB); PG8_STAGE(PG8_SA(0, 0), a2, voffA);
;             PG8_WAIT_V(8); PG8_WAIT_L(0); PG8_BAR; PG8_MMA(1, 0, At, B0); PG8_MMA(1, 1, At, B1); PG8_BAR; PG8_SCHED;
.LBB0_455:
	s_ashr_i32 s15, s14, 31
	s_lshl_b64 s[16:17], s[14:15], 19
	s_add_u32 s16, s74, s16
	s_addc_u32 s17, s75, s17
	s_and_b64 s[18:19], s[4:5], exec
	s_cselect_b32 s15, s17, s21
	s_cselect_b32 s69, s16, s20
	s_ashr_i32 s13, s12, 31
	s_lshl_b64 s[18:19], s[12:13], 19
	s_add_u32 s18, s28, s18
	s_addc_u32 s19, s29, s19
	s_and_b64 s[24:25], s[4:5], exec
	s_cselect_b32 s13, s19, s73
	s_cselect_b32 s70, s18, s72
	s_add_u32 s20, s20, 0x40080
	s_addc_u32 s21, s21, 0
	s_add_u32 s71, s72, 0x100
	s_addc_u32 s72, s73, 0
	s_mov_b32 s73, -2
	s_add_u32 s22, s20, 0xfffc0080
	s_addc_u32 s23, s21, -1
	s_add_i32 s76, 0, 0x10000
	s_cmp_eq_u32 s73, 12
	s_cselect_b32 s25, s15, s23
	s_cselect_b32 s24, s69, s22
	s_cselect_b32 s23, s13, s72
	s_cselect_b32 s22, s70, s71
	s_add_i32 s78, 0, 0x14000
	v_add_u32_e32 v140, s76, v158
	v_add_u32_e32 v154, s78, v158
	ds_read_b128 v[128:131], v140
	ds_read_b128 v[132:135], v140 offset:1024
	ds_read_b128 v[136:139], v140 offset:2048
	ds_read_b128 v[140:143], v140 offset:3072
	ds_read_b128 v[150:153], v154
	ds_read_b128 v[162:165], v154 offset:1024
	ds_read_b128 v[166:169], v154 offset:2048
	ds_read_b128 v[170:173], v154 offset:3072
	v_lshl_add_u64 v[154:155], s[20:21], 0, v[146:147]
	s_add_i32 m0, s37, 0xc000
	ds_read_b128 v[174:177], v160
	ds_read_b128 v[178:181], v160 offset:1024
	ds_read_b128 v[190:193], v160 offset:2048
	ds_read_b128 v[194:197], v160 offset:3072
	ds_read_b128 v[198:201], v160 offset:4096
	ds_read_b128 v[202:205], v160 offset:5120
	ds_read_b128 v[206:209], v160 offset:6144
	ds_read_b128 v[222:225], v160 offset:7168
	global_load_lds_dwordx4 v[154:155], off
	v_lshl_add_u64 v[154:155], s[20:21], 0, v[148:149]
	s_add_i32 m0, s37, 0xe000
	s_nop 0
	global_load_lds_dwordx4 v[154:155], off
	s_waitcnt vmcnt(8)
	s_waitcnt lgkmcnt(0)
	s_barrier
	s_setprio 1
	s_waitcnt lgkmcnt(0)
	v_mfma_f32_16x16x32_bf16 v[124:127], v[128:131], v[174:177], 0
	v_mfma_f32_16x16x32_bf16 v[120:123], v[136:139], v[174:177], 0
	v_mfma_f32_16x16x32_bf16 v[116:119], v[128:131], v[190:193], 0
	v_mfma_f32_16x16x32_bf16 v[112:115], v[136:139], v[190:193], 0
	v_mfma_f32_16x16x32_bf16 v[100:103], v[128:131], v[198:201], 0
	v_mfma_f32_16x16x32_bf16 v[88:91], v[136:139], v[198:201], 0
	v_mfma_f32_16x16x32_bf16 v[80:83], v[128:131], v[206:209], 0
	v_mfma_f32_16x16x32_bf16 v[72:75], v[136:139], v[206:209], 0
	v_mfma_f32_16x16x32_bf16 v[124:127], v[132:135], v[178:181], v[124:127]
	v_mfma_f32_16x16x32_bf16 v[120:123], v[140:143], v[178:181], v[120:123]
	v_mfma_f32_16x16x32_bf16 v[116:119], v[132:135], v[194:197], v[116:119]
	v_mfma_f32_16x16x32_bf16 v[112:115], v[140:143], v[194:197], v[112:115]
	v_mfma_f32_16x16x32_bf16 v[100:103], v[132:135], v[202:205], v[100:103]
	v_mfma_f32_16x16x32_bf16 v[88:91], v[140:143], v[202:205], v[88:91]
	v_mfma_f32_16x16x32_bf16 v[80:83], v[132:135], v[222:225], v[80:83]
	v_mfma_f32_16x16x32_bf16 v[72:75], v[140:143], v[222:225], v[72:75]
	s_setprio 0
	s_setprio 1
	v_mfma_f32_16x16x32_bf16 v[108:111], v[150:153], v[174:177], 0
	v_mfma_f32_16x16x32_bf16 v[104:107], v[166:169], v[174:177], 0
	v_mfma_f32_16x16x32_bf16 v[96:99], v[150:153], v[190:193], 0
	v_mfma_f32_16x16x32_bf16 v[92:95], v[166:169], v[190:193], 0
	v_mfma_f32_16x16x32_bf16 v[84:87], v[150:153], v[198:201], 0
	v_mfma_f32_16x16x32_bf16 v[76:79], v[166:169], v[198:201], 0
	v_mfma_f32_16x16x32_bf16 v[68:71], v[150:153], v[206:209], 0
	v_mfma_f32_16x16x32_bf16 v[64:67], v[166:169], v[206:209], 0
	v_mfma_f32_16x16x32_bf16 v[108:111], v[162:165], v[178:181], v[108:111]
	v_mfma_f32_16x16x32_bf16 v[104:107], v[170:173], v[178:181], v[104:107]
	v_mfma_f32_16x16x32_bf16 v[96:99], v[162:165], v[194:197], v[96:99]
	v_mfma_f32_16x16x32_bf16 v[92:95], v[170:173], v[194:197], v[92:95]
	v_mfma_f32_16x16x32_bf16 v[84:87], v[162:165], v[202:205], v[84:87]
	v_mfma_f32_16x16x32_bf16 v[76:79], v[170:173], v[202:205], v[76:79]
	v_mfma_f32_16x16x32_bf16 v[68:71], v[162:165], v[222:225], v[68:71]
	v_mfma_f32_16x16x32_bf16 v[64:67], v[170:173], v[222:225], v[64:67]
	s_setprio 0
	s_barrier
	s_add_i32 s76, s76, s36
	v_lshl_add_u64 v[154:155], s[22:23], 0, v[184:185]
	s_mov_b32 m0, s76
	ds_read_b128 v[174:177], v160 offset:16384
	ds_read_b128 v[178:181], v160 offset:17408
	ds_read_b128 v[190:193], v160 offset:18432
	ds_read_b128 v[194:197], v160 offset:19456
	ds_read_b128 v[198:201], v160 offset:20480
	ds_read_b128 v[202:205], v160 offset:21504
	ds_read_b128 v[206:209], v160 offset:22528
	ds_read_b128 v[222:225], v160 offset:23552
	global_load_lds_dwordx4 v[154:155], off
	s_add_i32 m0, s76, 0x2000
	s_add_u32 s76, s22, 0x40000
	v_lshl_add_u64 v[182:183], s[22:23], 0, v[144:145]
	s_addc_u32 s77, s23, 0
	s_add_i32 s78, s78, s36
	global_load_lds_dwordx4 v[182:183], off
	v_lshl_add_u64 v[186:187], s[76:77], 0, v[184:185]
	s_mov_b32 m0, s78
	v_lshl_add_u64 v[188:189], s[24:25], 0, v[144:145]
	global_load_lds_dwordx4 v[186:187], off
	v_lshl_add_u64 v[186:187], s[76:77], 0, v[144:145]
	s_add_i32 m0, s78, 0x2000
	s_nop 0
	global_load_lds_dwordx4 v[186:187], off
	v_lshl_add_u64 v[186:187], s[24:25], 0, v[184:185]
	s_mov_b32 m0, s37
	s_nop 0
	global_load_lds_dwordx4 v[186:187], off
	s_mov_b32 m0, s42
	s_nop 0
	global_load_lds_dwordx4 v[188:189], off
	s_waitcnt vmcnt(8)
	s_waitcnt lgkmcnt(0)
	s_barrier
; #define PG8_STAGE(bufoff, gbase, voff) do { _Pragma("unroll") for (int _i = 0; _i < 2; ++_i) \
;         __builtin_amdgcn_global_load_lds((const unsigned*)((const char*)(gbase) + (voff)[_i]), (PG8_LAS unsigned*)(lds + (bufoff) + ldsw + _i * 8192), 16, 0, 0); } while (0)
; #define PG8_LDA(dst, b, h) do { _Pragma("unroll") for (int m = 0; m < 4; ++m) _Pragma("unroll") for (int k = 0; k < 2; ++k) dst[m][k] = *(const PG8_LAS bf16x8*)(lds + PG8_SA(b, h) + aoff + m * 2048 + k * 1024); } while (0)
; #define PG8_LDB(dst, b, h) do { _Pragma("unroll") for (int n = 0; n < 2; ++n) _Pragma("unroll") for (int k = 0; k < 2; ++k) dst[n][k] = *(const PG8_LAS bf16x8*)(lds + PG8_SB(b, h) + boff + n * 2048 + k * 1024); } while (0)
; #define PG8_MMA(ai, bj, At, Bt) do { __builtin_amdgcn_s_setprio(1); _Pragma("unroll") for (int m = 0; m < 4; ++m) _Pragma("unroll") for (int n = 0; n < 2; ++n) _Pragma("unroll") for (int k = 0; k < 2; ++k) \
;         acc[ai][bj][m][n] = __builtin_amdgcn_mfma_f32_16x16x32_bf16(Bt[n][k], At[m][k], acc[ai][bj][m][n], 0, 0, 0); __builtin_amdgcn_s_setprio(0); } while (0)
; #define PG8_WAIT_V(n) asm volatile("s_waitcnt vmcnt(" #n ")" ::: "memory")
; #define PG8_WAIT_L(n) asm volatile("s_waitcnt lgkmcnt(" #n ")" ::: "memory")
; #define PG8_BAR __builtin_amdgcn_s_barrier()
; #define PG8_SCHED __builtin_amdgcn_sched_barrier(0)
; template <class Epi, class Sched, bool ALIGN_EPI = false, bool SP2 = false>
; __device__ __forceinline__ void gemm_phase(PG8_LAS unsigned char* lds, const Gemm g, const Sched& S, const Epi& E) {
;     ...
;             PG8_WAIT_V(8); PG8_WAIT_L(0); PG8_BAR; PG8_MMA(1, 0, At, B0); PG8_MMA(1, 1, At, B1); PG8_BAR; PG8_SCHED;
;             PG8_LDB(B0, 1, 0); PG8_LDB(B1, 1, 1); PG8_SCHED; PG8_LDA(At, 1, 0); PG8_STAGE(PG8_SA(0, 1), a2 + hstep, voffA);
;             PG8_WAIT_V(8); PG8_WAIT_L(0); PG8_BAR; PG8_MMA(0, 0, At, B0); PG8_MMA(0, 1, At, B1); PG8_BAR; PG8_SCHED;
	s_setprio 1
	s_waitcnt lgkmcnt(0)
	v_mfma_f32_16x16x32_bf16 v[60:63], v[128:131], v[174:177], 0
	v_mfma_f32_16x16x32_bf16 v[56:59], v[136:139], v[174:177], 0
	v_mfma_f32_16x16x32_bf16 v[48:51], v[128:131], v[190:193], 0
	v_mfma_f32_16x16x32_bf16 v[40:43], v[136:139], v[190:193], 0
	v_mfma_f32_16x16x32_bf16 v[32:35], v[128:131], v[198:201], 0
	v_mfma_f32_16x16x32_bf16 v[24:27], v[136:139], v[198:201], 0
	v_mfma_f32_16x16x32_bf16 v[16:19], v[128:131], v[206:209], 0
	v_mfma_f32_16x16x32_bf16 v[8:11], v[136:139], v[206:209], 0
	v_mfma_f32_16x16x32_bf16 v[60:63], v[132:135], v[178:181], v[60:63]
	v_mfma_f32_16x16x32_bf16 v[56:59], v[140:143], v[178:181], v[56:59]
	v_mfma_f32_16x16x32_bf16 v[48:51], v[132:135], v[194:197], v[48:51]
	v_mfma_f32_16x16x32_bf16 v[40:43], v[140:143], v[194:197], v[40:43]
	v_mfma_f32_16x16x32_bf16 v[32:35], v[132:135], v[202:205], v[32:35]
	v_mfma_f32_16x16x32_bf16 v[24:27], v[140:143], v[202:205], v[24:27]
	v_mfma_f32_16x16x32_bf16 v[16:19], v[132:135], v[222:225], v[16:19]
	v_mfma_f32_16x16x32_bf16 v[8:11], v[140:143], v[222:225], v[8:11]
	s_setprio 0
	s_setprio 1
	v_mfma_f32_16x16x32_bf16 v[52:55], v[150:153], v[174:177], 0
	v_mfma_f32_16x16x32_bf16 v[44:47], v[166:169], v[174:177], 0
	v_mfma_f32_16x16x32_bf16 v[36:39], v[150:153], v[190:193], 0
	v_mfma_f32_16x16x32_bf16 v[28:31], v[166:169], v[190:193], 0
	v_mfma_f32_16x16x32_bf16 v[20:23], v[150:153], v[198:201], 0
	v_mfma_f32_16x16x32_bf16 v[12:15], v[166:169], v[198:201], 0
	v_mfma_f32_16x16x32_bf16 v[4:7], v[150:153], v[206:209], 0
	v_mfma_f32_16x16x32_bf16 v[0:3], v[166:169], v[206:209], 0
	v_mfma_f32_16x16x32_bf16 v[52:55], v[162:165], v[178:181], v[52:55]
	v_mfma_f32_16x16x32_bf16 v[44:47], v[170:173], v[178:181], v[44:47]
	v_mfma_f32_16x16x32_bf16 v[36:39], v[162:165], v[194:197], v[36:39]
	v_mfma_f32_16x16x32_bf16 v[28:31], v[170:173], v[194:197], v[28:31]
	v_mfma_f32_16x16x32_bf16 v[20:23], v[162:165], v[202:205], v[20:23]
	v_mfma_f32_16x16x32_bf16 v[12:15], v[170:173], v[202:205], v[12:15]
	v_mfma_f32_16x16x32_bf16 v[4:7], v[162:165], v[222:225], v[4:7]
	v_mfma_f32_16x16x32_bf16 v[0:3], v[170:173], v[222:225], v[0:3]
	s_setprio 0
	s_barrier
	s_add_i32 s76, 0, 0x18000
	s_add_i32 s77, 0, 0x1c000
	v_add_u32_e32 v140, s76, v158
	v_add_u32_e32 v161, s77, v158
	ds_read_b128 v[128:131], v140
	ds_read_b128 v[132:135], v140 offset:1024
	ds_read_b128 v[136:139], v140 offset:2048
	ds_read_b128 v[140:143], v140 offset:3072
	ds_read_b128 v[150:153], v161
	ds_read_b128 v[162:165], v161 offset:1024
	ds_read_b128 v[166:169], v161 offset:2048
	ds_read_b128 v[170:173], v161 offset:3072
	s_add_u32 s24, s24, 0x40000
	s_addc_u32 s25, s25, 0
	s_mov_b32 m0, s43
	v_lshl_add_u64 v[210:211], s[24:25], 0, v[184:185]
	ds_read_b128 v[174:177], v160 offset:32768
	ds_read_b128 v[178:181], v160 offset:33792
	ds_read_b128 v[190:193], v160 offset:34816
	ds_read_b128 v[194:197], v160 offset:35840
	ds_read_b128 v[198:201], v160 offset:36864
	ds_read_b128 v[202:205], v160 offset:37888
	ds_read_b128 v[206:209], v160 offset:38912
	ds_read_b128 v[222:225], v160 offset:39936
	global_load_lds_dwordx4 v[210:211], off
	v_lshl_add_u64 v[210:211], s[24:25], 0, v[144:145]
	s_mov_b32 m0, s44
	s_nop 0
	global_load_lds_dwordx4 v[210:211], off
	s_waitcnt vmcnt(8)
	s_waitcnt lgkmcnt(0)
	s_barrier
	s_setprio 1
	s_waitcnt lgkmcnt(0)
	v_mfma_f32_16x16x32_bf16 v[124:127], v[128:131], v[174:177], v[124:127]
	v_mfma_f32_16x16x32_bf16 v[120:123], v[136:139], v[174:177], v[120:123]
	v_mfma_f32_16x16x32_bf16 v[116:119], v[128:131], v[190:193], v[116:119]
	v_mfma_f32_16x16x32_bf16 v[112:115], v[136:139], v[190:193], v[112:115]
	v_mfma_f32_16x16x32_bf16 v[100:103], v[128:131], v[198:201], v[100:103]
	v_mfma_f32_16x16x32_bf16 v[88:91], v[136:139], v[198:201], v[88:91]
	v_mfma_f32_16x16x32_bf16 v[80:83], v[128:131], v[206:209], v[80:83]
	v_mfma_f32_16x16x32_bf16 v[72:75], v[136:139], v[206:209], v[72:75]
	v_mfma_f32_16x16x32_bf16 v[124:127], v[132:135], v[178:181], v[124:127]
	v_mfma_f32_16x16x32_bf16 v[120:123], v[140:143], v[178:181], v[120:123]
	v_mfma_f32_16x16x32_bf16 v[116:119], v[132:135], v[194:197], v[116:119]
	v_mfma_f32_16x16x32_bf16 v[112:115], v[140:143], v[194:197], v[112:115]
	v_mfma_f32_16x16x32_bf16 v[100:103], v[132:135], v[202:205], v[100:103]
	v_mfma_f32_16x16x32_bf16 v[88:91], v[140:143], v[202:205], v[88:91]
	v_mfma_f32_16x16x32_bf16 v[80:83], v[132:135], v[222:225], v[80:83]
	v_mfma_f32_16x16x32_bf16 v[72:75], v[140:143], v[222:225], v[72:75]
	s_setprio 0
	s_setprio 1
	v_mfma_f32_16x16x32_bf16 v[108:111], v[150:153], v[174:177], v[108:111]
	v_mfma_f32_16x16x32_bf16 v[104:107], v[166:169], v[174:177], v[104:107]
	v_mfma_f32_16x16x32_bf16 v[96:99], v[150:153], v[190:193], v[96:99]
	v_mfma_f32_16x16x32_bf16 v[92:95], v[166:169], v[190:193], v[92:95]
	v_mfma_f32_16x16x32_bf16 v[84:87], v[150:153], v[198:201], v[84:87]
	v_mfma_f32_16x16x32_bf16 v[76:79], v[166:169], v[198:201], v[76:79]
	v_mfma_f32_16x16x32_bf16 v[68:71], v[150:153], v[206:209], v[68:71]
	v_mfma_f32_16x16x32_bf16 v[64:67], v[166:169], v[206:209], v[64:67]
	v_mfma_f32_16x16x32_bf16 v[108:111], v[162:165], v[178:181], v[108:111]
	v_mfma_f32_16x16x32_bf16 v[104:107], v[170:173], v[178:181], v[104:107]
	v_mfma_f32_16x16x32_bf16 v[96:99], v[162:165], v[194:197], v[96:99]
	v_mfma_f32_16x16x32_bf16 v[92:95], v[170:173], v[194:197], v[92:95]
	v_mfma_f32_16x16x32_bf16 v[84:87], v[162:165], v[202:205], v[84:87]
	v_mfma_f32_16x16x32_bf16 v[76:79], v[170:173], v[202:205], v[76:79]
	v_mfma_f32_16x16x32_bf16 v[68:71], v[162:165], v[222:225], v[68:71]
	v_mfma_f32_16x16x32_bf16 v[64:67], v[170:173], v[222:225], v[64:67]
	s_setprio 0
	s_barrier
; #define PG8_STAGE(bufoff, gbase, voff) do { _Pragma("unroll") for (int _i = 0; _i < 2; ++_i) \
;         __builtin_amdgcn_global_load_lds((const unsigned*)((const char*)(gbase) + (voff)[_i]), (PG8_LAS unsigned*)(lds + (bufoff) + ldsw + _i * 8192), 16, 0, 0); } while (0)
; #define PG8_LDA(dst, b, h) do { _Pragma("unroll") for (int m = 0; m < 4; ++m) _Pragma("unroll") for (int k = 0; k < 2; ++k) dst[m][k] = *(const PG8_LAS bf16x8*)(lds + PG8_SA(b, h) + aoff + m * 2048 + k * 1024); } while (0)
; #define PG8_MMA(ai, bj, At, Bt) do { __builtin_amdgcn_s_setprio(1); _Pragma("unroll") for (int m = 0; m < 4; ++m) _Pragma("unroll") for (int n = 0; n < 2; ++n) _Pragma("unroll") for (int k = 0; k < 2; ++k) \
;         acc[ai][bj][m][n] = __builtin_amdgcn_mfma_f32_16x16x32_bf16(Bt[n][k], At[m][k], acc[ai][bj][m][n], 0, 0, 0); __builtin_amdgcn_s_setprio(0); } while (0)
; #define PG8_WAIT_V(n) asm volatile("s_waitcnt vmcnt(" #n ")" ::: "memory")
; #define PG8_WAIT_L(n) asm volatile("s_waitcnt lgkmcnt(" #n ")" ::: "memory")
; #define PG8_BAR __builtin_amdgcn_s_barrier()
; #define PG8_SCHED __builtin_amdgcn_sched_barrier(0)
; template <class Epi, class Sched, bool ALIGN_EPI = false, bool SP2 = false>
; __device__ __forceinline__ void gemm_phase(PG8_LAS unsigned char* lds, const Gemm g, const Sched& S, const Epi& E) {
;     ...
;         for (int t = 0; t < nt; t += 2) {
;             const bool last = (t == nt - 2);
;     ...
;             PG8_LDA(At, 1, 1); PG8_STAGE(PG8_SB(1, 0), b3, voffB); PG8_STAGE(PG8_SB(1, 1), b3 + hstep, voffB); PG8_STAGE(PG8_SA(1, 0), a3, voffA);
;             PG8_WAIT_V(8); PG8_WAIT_L(0); PG8_BAR; PG8_MMA(1, 0, At, B0); PG8_MMA(1, 1, At, B1); PG8_BAR; PG8_SCHED;
	s_add_i32 s24, s76, s36
	v_lshl_add_u64 v[154:155], v[154:155], 0, s[30:31]
	s_mov_b32 m0, s24
	ds_read_b128 v[174:177], v160 offset:49152
	ds_read_b128 v[178:181], v160 offset:50176
	ds_read_b128 v[190:193], v160 offset:51200
	ds_read_b128 v[194:197], v160 offset:52224
	ds_read_b128 v[198:201], v160 offset:53248
	ds_read_b128 v[202:205], v160 offset:54272
	ds_read_b128 v[206:209], v160 offset:55296
	ds_read_b128 v[222:225], v160 offset:56320
	global_load_lds_dwordx4 v[154:155], off
	s_add_i32 m0, s24, 0x2000
	s_add_u32 s22, s22, 0x40080
	v_lshl_add_u64 v[154:155], v[182:183], 0, s[30:31]
	s_addc_u32 s23, s23, 0
	s_add_i32 s24, s77, s36
	global_load_lds_dwordx4 v[154:155], off
	v_lshl_add_u64 v[154:155], s[22:23], 0, v[184:185]
	s_mov_b32 m0, s24
	s_nop 0
	global_load_lds_dwordx4 v[154:155], off
	v_lshl_add_u64 v[154:155], s[22:23], 0, v[144:145]
	s_add_i32 m0, s24, 0x2000
	s_nop 0
	global_load_lds_dwordx4 v[154:155], off
	v_lshl_add_u64 v[154:155], v[186:187], 0, s[30:31]
	s_mov_b32 m0, s47
	s_nop 0
	global_load_lds_dwordx4 v[154:155], off
	v_lshl_add_u64 v[154:155], v[188:189], 0, s[30:31]
	s_mov_b32 m0, s48
	s_nop 0
	global_load_lds_dwordx4 v[154:155], off
	s_waitcnt vmcnt(8)
	s_waitcnt lgkmcnt(0)
	s_barrier
	s_setprio 1
	s_waitcnt lgkmcnt(0)
	v_mfma_f32_16x16x32_bf16 v[60:63], v[128:131], v[174:177], v[60:63]
	v_mfma_f32_16x16x32_bf16 v[56:59], v[136:139], v[174:177], v[56:59]
	v_mfma_f32_16x16x32_bf16 v[48:51], v[128:131], v[190:193], v[48:51]
	v_mfma_f32_16x16x32_bf16 v[40:43], v[136:139], v[190:193], v[40:43]
	v_mfma_f32_16x16x32_bf16 v[32:35], v[128:131], v[198:201], v[32:35]
	v_mfma_f32_16x16x32_bf16 v[24:27], v[136:139], v[198:201], v[24:27]
	v_mfma_f32_16x16x32_bf16 v[16:19], v[128:131], v[206:209], v[16:19]
	v_mfma_f32_16x16x32_bf16 v[8:11], v[136:139], v[206:209], v[8:11]
	v_mfma_f32_16x16x32_bf16 v[60:63], v[132:135], v[178:181], v[60:63]
	v_mfma_f32_16x16x32_bf16 v[56:59], v[140:143], v[178:181], v[56:59]
	v_mfma_f32_16x16x32_bf16 v[48:51], v[132:135], v[194:197], v[48:51]
	v_mfma_f32_16x16x32_bf16 v[40:43], v[140:143], v[194:197], v[40:43]
	v_mfma_f32_16x16x32_bf16 v[32:35], v[132:135], v[202:205], v[32:35]
	v_mfma_f32_16x16x32_bf16 v[24:27], v[140:143], v[202:205], v[24:27]
	v_mfma_f32_16x16x32_bf16 v[16:19], v[132:135], v[222:225], v[16:19]
	v_mfma_f32_16x16x32_bf16 v[8:11], v[140:143], v[222:225], v[8:11]
	s_setprio 0
	s_setprio 1
	v_mfma_f32_16x16x32_bf16 v[52:55], v[150:153], v[174:177], v[52:55]
	v_mfma_f32_16x16x32_bf16 v[44:47], v[166:169], v[174:177], v[44:47]
	v_mfma_f32_16x16x32_bf16 v[36:39], v[150:153], v[190:193], v[36:39]
	v_mfma_f32_16x16x32_bf16 v[28:31], v[166:169], v[190:193], v[28:31]
	v_mfma_f32_16x16x32_bf16 v[20:23], v[150:153], v[198:201], v[20:23]
	v_mfma_f32_16x16x32_bf16 v[12:15], v[166:169], v[198:201], v[12:15]
	v_mfma_f32_16x16x32_bf16 v[4:7], v[150:153], v[206:209], v[4:7]
	v_mfma_f32_16x16x32_bf16 v[0:3], v[166:169], v[206:209], v[0:3]
	v_mfma_f32_16x16x32_bf16 v[52:55], v[162:165], v[178:181], v[52:55]
	v_mfma_f32_16x16x32_bf16 v[44:47], v[170:173], v[178:181], v[44:47]
	v_mfma_f32_16x16x32_bf16 v[36:39], v[162:165], v[194:197], v[36:39]
	v_mfma_f32_16x16x32_bf16 v[28:31], v[170:173], v[194:197], v[28:31]
	v_mfma_f32_16x16x32_bf16 v[20:23], v[162:165], v[202:205], v[20:23]
	v_mfma_f32_16x16x32_bf16 v[12:15], v[170:173], v[202:205], v[12:15]
	v_mfma_f32_16x16x32_bf16 v[4:7], v[162:165], v[222:225], v[4:7]
	v_mfma_f32_16x16x32_bf16 v[0:3], v[170:173], v[222:225], v[0:3]
	s_setprio 0
	s_barrier
	s_add_i32 s73, s73, 2
	s_add_u32 s20, s20, 0x100
	s_addc_u32 s21, s21, 0
	s_add_u32 s71, s71, 0x100
	s_addc_u32 s72, s72, 0
	s_cmp_gt_u32 s73, 13
	s_cbranch_scc0 .LBB0_456
	s_branch .Lgzero3_done

; #define PG8_BAR __builtin_amdgcn_s_barrier()
; template <class Epi, class Sched, bool ALIGN_EPI = false, bool SP2 = false>
; __device__ __forceinline__ void gemm_phase(PG8_LAS unsigned char* lds, const Gemm g, const Sched& S, const Epi& E) {
;     ...
;         if constexpr (ALIGN_EPI) { if (wr == 0) PG8_BAR; }
;         if constexpr (!Epi::AFTER_DRAIN) { E(acc, cur, wr, wc, fr, fq); S.done(cur); }
.Lgzero3_done:
	s_and_b64 vcc, exec, s[10:11]
	s_cbranch_vccz .LBB0_459
	s_barrier
